# RWKV RA P3 forward substitution rewritten: LDS reads software-pipelined 8 deep, packed f32 FMA, same arithmetic order
# speedup vs baseline: 1.0115x; 1.0115x over previous
; #define LAS __attribute__((address_space(3)))
; __device__ __forceinline__ bf16_t f2bf(float f) { unsigned u = __float_as_uint(f); u += 0x7FFFu + ((u >> 16) & 1u); return (bf16_t)(u >> 16); }
; __device__ __forceinline__ void phase_rwkv_ra(const Ctx& c, int p, int l) {
;     ...
;         if (w == 0) {
;             float M[64];
; #pragma unroll
;             for (int tt = 0; tt < 64; ++tt) {
;                 float a4[4] = {(lane == tt) ? 1.f : 0.f, 0.f, 0.f, 0.f};
; #pragma unroll
;                 for (int p4 = 0; p4 < (tt + 3) / 4; ++p4) {
;                     const f32x4 nv = *(const LAS f32x4*)(NfT + tt * 68 + 4 * p4);
; #pragma unroll
;                     for (int e = 0; e < 4; ++e) if (4 * p4 + e < tt) a4[e] += M[4 * p4 + e] * nv[e];
;                 }
;                 const float a = (a4[0] + a4[1]) + (a4[2] + a4[3]);
;                 M[tt] = a;
;                 MinvT[tt * RS + lane] = f2bf(a);
;             }
.LBB0_1319:
	s_waitcnt vmcnt(0)
	v_add_u32_e32 v186, 0x12000, v121
	ds_read_b128 v[8:11], v186 offset:272
	ds_read_b128 v[12:15], v186 offset:544
	ds_read_b128 v[16:19], v186 offset:816
	ds_read_b128 v[20:23], v186 offset:1088
	ds_read_b128 v[24:27], v186 offset:1360
	ds_read_b128 v[32:35], v186 offset:1376
	ds_read_b128 v[36:39], v186 offset:1632
	ds_read_b128 v[80:83], v186 offset:1648
	v_lshl_add_u32 v29, v88, 1, v74
	v_mov_b32_e32 v85, 0
	v_cmp_eq_u32_e32 vcc, 0, v88
	s_nop 1
	v_cndmask_b32_e64 v42, 0, 1.0, vcc
	v_cmp_eq_u32_e32 vcc, 1, v88
	v_cvt_pk_bf16_f32 v30, v42, v42
	ds_write_b16 v29, v30
	v_cndmask_b32_e64 v84, 0, 1.0, vcc
	s_waitcnt lgkmcnt(8)
	v_fma_f32 v138, v42, v8, v84
	v_cmp_eq_u32_e32 vcc, 2, v88
	ds_read_b128 v[8:11], v186 offset:1904
	v_mov_b32_e32 v43, v138
	v_cndmask_b32_e64 v84, 0, 1.0, vcc
	v_cvt_pk_bf16_f32 v30, v43, v43
	ds_write_b16 v29, v30 offset:144
	s_waitcnt lgkmcnt(9)
	v_pk_fma_f32 v[138:139], v[42:43], v[12:13], v[84:85]
	v_cmp_eq_u32_e32 vcc, 3, v88
	ds_read_b128 v[12:15], v186 offset:1920
	v_add_f32_e32 v187, v138, v139
	v_mov_b32_e32 v44, v187
	v_cndmask_b32_e64 v84, 0, 1.0, vcc
	v_cvt_pk_bf16_f32 v30, v44, v44
	ds_write_b16 v29, v30 offset:288
	s_waitcnt lgkmcnt(10)
	v_pk_fma_f32 v[138:139], v[42:43], v[16:17], v[84:85]
	v_cmp_eq_u32_e32 vcc, 4, v88
	v_mul_f32_e32 v184, v44, v18
	ds_read_b128 v[16:19], v186 offset:2176
	v_add_f32_e32 v187, v138, v139
	v_add_f32_e32 v45, v187, v184
	v_cndmask_b32_e64 v84, 0, 1.0, vcc
	v_cvt_pk_bf16_f32 v30, v45, v45
	ds_write_b16 v29, v30 offset:432
	s_waitcnt lgkmcnt(11)
	v_pk_fma_f32 v[138:139], v[42:43], v[20:21], v[84:85]
	v_cmp_eq_u32_e32 vcc, 5, v88
	v_pk_mul_f32 v[184:185], v[44:45], v[22:23]
	ds_read_b128 v[20:23], v186 offset:2192
	v_add_f32_e32 v187, v138, v139
	v_add_f32_e32 v30, v184, v185
	v_add_f32_e32 v46, v187, v30
	v_cndmask_b32_e64 v84, 0, 1.0, vcc
	v_cvt_pk_bf16_f32 v30, v46, v46
	ds_write_b16 v29, v30 offset:576
	s_waitcnt lgkmcnt(12)
	v_pk_fma_f32 v[138:139], v[42:43], v[24:25], v[84:85]
	v_cmp_eq_u32_e32 vcc, 6, v88
	v_pk_mul_f32 v[184:185], v[44:45], v[26:27]
	ds_read_b128 v[24:27], v186 offset:2448
	s_waitcnt lgkmcnt(12)
	v_fmac_f32_e32 v138, v46, v32
	ds_read_b128 v[32:35], v186 offset:2464
	v_add_f32_e32 v187, v138, v139
	v_add_f32_e32 v30, v184, v185
	v_add_f32_e32 v47, v187, v30
	v_cndmask_b32_e64 v84, 0, 1.0, vcc
	v_cvt_pk_bf16_f32 v30, v47, v47
	ds_write_b16 v29, v30 offset:720
	s_waitcnt lgkmcnt(13)
	v_pk_fma_f32 v[138:139], v[42:43], v[36:37], v[84:85]
	v_cmp_eq_u32_e32 vcc, 7, v88
	v_pk_mul_f32 v[184:185], v[44:45], v[38:39]
	ds_read_b128 v[36:39], v186 offset:2480
	s_waitcnt lgkmcnt(13)
	v_pk_fma_f32 v[138:139], v[46:47], v[80:81], v[138:139]
	ds_read_b128 v[80:83], v186 offset:2720
	v_add_f32_e32 v187, v138, v139
	v_add_f32_e32 v30, v184, v185
	v_add_f32_e32 v48, v187, v30
	v_cndmask_b32_e64 v84, 0, 1.0, vcc
	v_cvt_pk_bf16_f32 v30, v48, v48
	ds_write_b16 v29, v30 offset:864
	s_waitcnt lgkmcnt(13)
	v_pk_fma_f32 v[138:139], v[42:43], v[8:9], v[84:85]
	v_cmp_eq_u32_e32 vcc, 8, v88
	v_pk_mul_f32 v[184:185], v[44:45], v[10:11]
	ds_read_b128 v[8:11], v186 offset:2736
	s_waitcnt lgkmcnt(12)
	v_pk_fma_f32 v[138:139], v[46:47], v[12:13], v[138:139]
	v_fmac_f32_e32 v184, v48, v14
	ds_read_b128 v[12:15], v186 offset:2752
	v_add_f32_e32 v187, v138, v139
	v_add_f32_e32 v30, v184, v185
	v_add_f32_e32 v49, v187, v30
	v_cndmask_b32_e64 v84, 0, 1.0, vcc
	v_cvt_pk_bf16_f32 v30, v49, v49
	ds_write_b16 v29, v30 offset:1008
	s_waitcnt lgkmcnt(12)
	v_pk_fma_f32 v[138:139], v[42:43], v[16:17], v[84:85]
	v_cmp_eq_u32_e32 vcc, 9, v88
	v_pk_mul_f32 v[184:185], v[44:45], v[18:19]
	ds_read_b128 v[16:19], v186 offset:2992
	s_waitcnt lgkmcnt(11)
	v_pk_fma_f32 v[138:139], v[46:47], v[20:21], v[138:139]
	v_pk_fma_f32 v[184:185], v[48:49], v[22:23], v[184:185]
	ds_read_b128 v[20:23], v186 offset:3008
	v_add_f32_e32 v187, v138, v139
	v_add_f32_e32 v30, v184, v185
	v_add_f32_e32 v50, v187, v30
	v_cndmask_b32_e64 v84, 0, 1.0, vcc
	v_cvt_pk_bf16_f32 v30, v50, v50
	ds_write_b16 v29, v30 offset:1152
	s_waitcnt lgkmcnt(11)
	v_pk_fma_f32 v[138:139], v[42:43], v[24:25], v[84:85]
	v_cmp_eq_u32_e32 vcc, 10, v88
	v_pk_mul_f32 v[184:185], v[44:45], v[26:27]
	ds_read_b128 v[24:27], v186 offset:3024
	s_waitcnt lgkmcnt(11)
	v_pk_fma_f32 v[138:139], v[46:47], v[32:33], v[138:139]
	v_pk_fma_f32 v[184:185], v[48:49], v[34:35], v[184:185]
	ds_read_b128 v[32:35], v186 offset:3264
	s_waitcnt lgkmcnt(10)
	v_fmac_f32_e32 v138, v50, v36
	ds_read_b128 v[36:39], v186 offset:3280
	v_add_f32_e32 v187, v138, v139
	v_add_f32_e32 v30, v184, v185
	v_add_f32_e32 v51, v187, v30
	v_cndmask_b32_e64 v84, 0, 1.0, vcc
	v_cvt_pk_bf16_f32 v30, v51, v51
	ds_write_b16 v29, v30 offset:1296
	s_waitcnt lgkmcnt(11)
	v_pk_fma_f32 v[138:139], v[42:43], v[80:81], v[84:85]
	v_cmp_eq_u32_e32 vcc, 11, v88
	v_pk_mul_f32 v[184:185], v[44:45], v[82:83]
	ds_read_b128 v[80:83], v186 offset:3296
	s_waitcnt lgkmcnt(10)
	v_pk_fma_f32 v[138:139], v[46:47], v[8:9], v[138:139]
	v_pk_fma_f32 v[184:185], v[48:49], v[10:11], v[184:185]
	ds_read_b128 v[8:11], v186 offset:3536
	s_waitcnt lgkmcnt(10)
	v_pk_fma_f32 v[138:139], v[50:51], v[12:13], v[138:139]
	ds_read_b128 v[12:15], v186 offset:3552
	v_add_f32_e32 v187, v138, v139
	v_add_f32_e32 v30, v184, v185
	v_add_f32_e32 v52, v187, v30
	v_cndmask_b32_e64 v84, 0, 1.0, vcc
	v_cvt_pk_bf16_f32 v30, v52, v52
	ds_write_b16 v29, v30 offset:1440
	s_waitcnt lgkmcnt(10)
	v_pk_fma_f32 v[138:139], v[42:43], v[16:17], v[84:85]
	v_cmp_eq_u32_e32 vcc, 12, v88
	v_pk_mul_f32 v[184:185], v[44:45], v[18:19]
	ds_read_b128 v[16:19], v186 offset:3568
	s_waitcnt lgkmcnt(10)
; #define LAS __attribute__((address_space(3)))
; __device__ __forceinline__ bf16_t f2bf(float f) { unsigned u = __float_as_uint(f); u += 0x7FFFu + ((u >> 16) & 1u); return (bf16_t)(u >> 16); }
; __device__ __forceinline__ void phase_rwkv_ra(const Ctx& c, int p, int l) {
;     ...
;         if (w == 0) {
;             float M[64];
; #pragma unroll
;             for (int tt = 0; tt < 64; ++tt) {
;                 float a4[4] = {(lane == tt) ? 1.f : 0.f, 0.f, 0.f, 0.f};
; #pragma unroll
;                 for (int p4 = 0; p4 < (tt + 3) / 4; ++p4) {
;                     const f32x4 nv = *(const LAS f32x4*)(NfT + tt * 68 + 4 * p4);
; #pragma unroll
;                     for (int e = 0; e < 4; ++e) if (4 * p4 + e < tt) a4[e] += M[4 * p4 + e] * nv[e];
;                 }
;                 const float a = (a4[0] + a4[1]) + (a4[2] + a4[3]);
;                 M[tt] = a;
;                 MinvT[tt * RS + lane] = f2bf(a);
;             }
	v_pk_fma_f32 v[138:139], v[46:47], v[20:21], v[138:139]
	v_pk_fma_f32 v[184:185], v[48:49], v[22:23], v[184:185]
	ds_read_b128 v[20:23], v186 offset:3584
	s_waitcnt lgkmcnt(9)
	v_pk_fma_f32 v[138:139], v[50:51], v[24:25], v[138:139]
	v_fmac_f32_e32 v184, v52, v26
	ds_read_b128 v[24:27], v186 offset:3808
	v_add_f32_e32 v187, v138, v139
	v_add_f32_e32 v30, v184, v185
	v_add_f32_e32 v53, v187, v30
	v_cndmask_b32_e64 v84, 0, 1.0, vcc
	v_cvt_pk_bf16_f32 v30, v53, v53
	ds_write_b16 v29, v30 offset:1584
	s_waitcnt lgkmcnt(10)
	v_pk_fma_f32 v[138:139], v[42:43], v[32:33], v[84:85]
	v_cmp_eq_u32_e32 vcc, 13, v88
	v_pk_mul_f32 v[184:185], v[44:45], v[34:35]
	ds_read_b128 v[32:35], v186 offset:3824
	s_waitcnt lgkmcnt(10)
	v_pk_fma_f32 v[138:139], v[46:47], v[36:37], v[138:139]
	v_pk_fma_f32 v[184:185], v[48:49], v[38:39], v[184:185]
	ds_read_b128 v[36:39], v186 offset:3840
	s_waitcnt lgkmcnt(9)
	v_pk_fma_f32 v[138:139], v[50:51], v[80:81], v[138:139]
	v_pk_fma_f32 v[184:185], v[52:53], v[82:83], v[184:185]
	ds_read_b128 v[80:83], v186 offset:3856
	v_add_f32_e32 v187, v138, v139
	v_add_f32_e32 v30, v184, v185
	v_add_f32_e32 v54, v187, v30
	v_cndmask_b32_e64 v84, 0, 1.0, vcc
	v_cvt_pk_bf16_f32 v30, v54, v54
	ds_write_b16 v29, v30 offset:1728
	s_waitcnt lgkmcnt(10)
	v_pk_fma_f32 v[138:139], v[42:43], v[8:9], v[84:85]
	v_cmp_eq_u32_e32 vcc, 14, v88
	v_pk_mul_f32 v[184:185], v[44:45], v[10:11]
	ds_read_b128 v[8:11], v186 offset:4080
	s_waitcnt lgkmcnt(10)
	v_pk_fma_f32 v[138:139], v[46:47], v[12:13], v[138:139]
	v_pk_fma_f32 v[184:185], v[48:49], v[14:15], v[184:185]
	ds_read_b128 v[12:15], v186 offset:4096
	s_waitcnt lgkmcnt(9)
	v_pk_fma_f32 v[138:139], v[50:51], v[16:17], v[138:139]
	v_pk_fma_f32 v[184:185], v[52:53], v[18:19], v[184:185]
	ds_read_b128 v[16:19], v186 offset:4112
	s_waitcnt lgkmcnt(9)
	v_fmac_f32_e32 v138, v54, v20
	ds_read_b128 v[20:23], v186 offset:4128
	v_add_f32_e32 v187, v138, v139
	v_add_f32_e32 v30, v184, v185
	v_add_f32_e32 v55, v187, v30
	v_cndmask_b32_e64 v84, 0, 1.0, vcc
	v_cvt_pk_bf16_f32 v30, v55, v55
	ds_write_b16 v29, v30 offset:1872
	s_waitcnt lgkmcnt(10)
	v_pk_fma_f32 v[138:139], v[42:43], v[24:25], v[84:85]
	v_cmp_eq_u32_e32 vcc, 15, v88
	v_pk_mul_f32 v[184:185], v[44:45], v[26:27]
	ds_read_b128 v[24:27], v186 offset:4352
	s_waitcnt lgkmcnt(9)
	v_pk_fma_f32 v[138:139], v[46:47], v[32:33], v[138:139]
	v_pk_fma_f32 v[184:185], v[48:49], v[34:35], v[184:185]
	ds_read_b128 v[32:35], v186 offset:4368
	s_waitcnt lgkmcnt(9)
	v_pk_fma_f32 v[138:139], v[50:51], v[36:37], v[138:139]
	v_pk_fma_f32 v[184:185], v[52:53], v[38:39], v[184:185]
	ds_read_b128 v[36:39], v186 offset:4384
	s_waitcnt lgkmcnt(9)
	v_pk_fma_f32 v[138:139], v[54:55], v[80:81], v[138:139]
	ds_read_b128 v[80:83], v186 offset:4400
	v_add_f32_e32 v187, v138, v139
	v_add_f32_e32 v30, v184, v185
	v_add_f32_e32 v56, v187, v30
	v_cndmask_b32_e64 v84, 0, 1.0, vcc
	v_cvt_pk_bf16_f32 v30, v56, v56
	ds_write_b16 v29, v30 offset:2016
	s_waitcnt lgkmcnt(9)
	v_pk_fma_f32 v[138:139], v[42:43], v[8:9], v[84:85]
	v_cmp_eq_u32_e32 vcc, 16, v88
	v_pk_mul_f32 v[184:185], v[44:45], v[10:11]
	ds_read_b128 v[8:11], v186 offset:4624
	s_waitcnt lgkmcnt(9)
	v_pk_fma_f32 v[138:139], v[46:47], v[12:13], v[138:139]
	v_pk_fma_f32 v[184:185], v[48:49], v[14:15], v[184:185]
	ds_read_b128 v[12:15], v186 offset:4640
	s_waitcnt lgkmcnt(9)
	v_pk_fma_f32 v[138:139], v[50:51], v[16:17], v[138:139]
	v_pk_fma_f32 v[184:185], v[52:53], v[18:19], v[184:185]
	ds_read_b128 v[16:19], v186 offset:4656
	s_waitcnt lgkmcnt(9)
	v_pk_fma_f32 v[138:139], v[54:55], v[20:21], v[138:139]
	v_fmac_f32_e32 v184, v56, v22
	ds_read_b128 v[20:23], v186 offset:4672
	v_add_f32_e32 v187, v138, v139
	v_add_f32_e32 v30, v184, v185
	v_add_f32_e32 v57, v187, v30
	v_cndmask_b32_e64 v84, 0, 1.0, vcc
	v_cvt_pk_bf16_f32 v30, v57, v57
	ds_write_b16 v29, v30 offset:2160
	s_waitcnt lgkmcnt(9)
	v_pk_fma_f32 v[138:139], v[42:43], v[24:25], v[84:85]
	v_cmp_eq_u32_e32 vcc, 17, v88
	v_pk_mul_f32 v[184:185], v[44:45], v[26:27]
	ds_read_b128 v[24:27], v186 offset:4688
	s_waitcnt lgkmcnt(9)
	v_pk_fma_f32 v[138:139], v[46:47], v[32:33], v[138:139]
	v_pk_fma_f32 v[184:185], v[48:49], v[34:35], v[184:185]
	ds_read_b128 v[32:35], v186 offset:4896
	s_waitcnt lgkmcnt(9)
	v_pk_fma_f32 v[138:139], v[50:51], v[36:37], v[138:139]
	v_pk_fma_f32 v[184:185], v[52:53], v[38:39], v[184:185]
	ds_read_b128 v[36:39], v186 offset:4912
	s_waitcnt lgkmcnt(9)
	v_pk_fma_f32 v[138:139], v[54:55], v[80:81], v[138:139]
	v_pk_fma_f32 v[184:185], v[56:57], v[82:83], v[184:185]
	ds_read_b128 v[80:83], v186 offset:4928
	v_add_f32_e32 v187, v138, v139
	v_add_f32_e32 v30, v184, v185
	v_add_f32_e32 v58, v187, v30
	v_cndmask_b32_e64 v84, 0, 1.0, vcc
	v_cvt_pk_bf16_f32 v30, v58, v58
	ds_write_b16 v29, v30 offset:2304
	s_waitcnt lgkmcnt(9)
	v_pk_fma_f32 v[138:139], v[42:43], v[8:9], v[84:85]
	v_cmp_eq_u32_e32 vcc, 18, v88
	v_pk_mul_f32 v[184:185], v[44:45], v[10:11]
	ds_read_b128 v[8:11], v186 offset:4944
	s_waitcnt lgkmcnt(9)
	v_pk_fma_f32 v[138:139], v[46:47], v[12:13], v[138:139]
	v_pk_fma_f32 v[184:185], v[48:49], v[14:15], v[184:185]
	ds_read_b128 v[12:15], v186 offset:4960
	s_waitcnt lgkmcnt(9)
	v_pk_fma_f32 v[138:139], v[50:51], v[16:17], v[138:139]
	v_pk_fma_f32 v[184:185], v[52:53], v[18:19], v[184:185]
	ds_read_b128 v[16:19], v186 offset:5168
	s_waitcnt lgkmcnt(9)
	v_pk_fma_f32 v[138:139], v[54:55], v[20:21], v[138:139]
	v_pk_fma_f32 v[184:185], v[56:57], v[22:23], v[184:185]
	ds_read_b128 v[20:23], v186 offset:5184
	s_waitcnt lgkmcnt(8)
; #define LAS __attribute__((address_space(3)))
; __device__ __forceinline__ bf16_t f2bf(float f) { unsigned u = __float_as_uint(f); u += 0x7FFFu + ((u >> 16) & 1u); return (bf16_t)(u >> 16); }
; __device__ __forceinline__ void phase_rwkv_ra(const Ctx& c, int p, int l) {
;     ...
;         if (w == 0) {
;             float M[64];
; #pragma unroll
;             for (int tt = 0; tt < 64; ++tt) {
;                 float a4[4] = {(lane == tt) ? 1.f : 0.f, 0.f, 0.f, 0.f};
; #pragma unroll
;                 for (int p4 = 0; p4 < (tt + 3) / 4; ++p4) {
;                     const f32x4 nv = *(const LAS f32x4*)(NfT + tt * 68 + 4 * p4);
; #pragma unroll
;                     for (int e = 0; e < 4; ++e) if (4 * p4 + e < tt) a4[e] += M[4 * p4 + e] * nv[e];
;                 }
;                 const float a = (a4[0] + a4[1]) + (a4[2] + a4[3]);
;                 M[tt] = a;
;                 MinvT[tt * RS + lane] = f2bf(a);
;             }
	v_fmac_f32_e32 v138, v58, v24
	ds_read_b128 v[24:27], v186 offset:5200
	v_add_f32_e32 v187, v138, v139
	v_add_f32_e32 v30, v184, v185
	v_add_f32_e32 v59, v187, v30
	v_cndmask_b32_e64 v84, 0, 1.0, vcc
	v_cvt_pk_bf16_f32 v30, v59, v59
	ds_write_b16 v29, v30 offset:2448
	s_waitcnt lgkmcnt(9)
	v_pk_fma_f32 v[138:139], v[42:43], v[32:33], v[84:85]
	v_cmp_eq_u32_e32 vcc, 19, v88
	v_pk_mul_f32 v[184:185], v[44:45], v[34:35]
	ds_read_b128 v[32:35], v186 offset:5216
	s_waitcnt lgkmcnt(9)
	v_pk_fma_f32 v[138:139], v[46:47], v[36:37], v[138:139]
	v_pk_fma_f32 v[184:185], v[48:49], v[38:39], v[184:185]
	ds_read_b128 v[36:39], v186 offset:5232
	s_waitcnt lgkmcnt(9)
	v_pk_fma_f32 v[138:139], v[50:51], v[80:81], v[138:139]
	v_pk_fma_f32 v[184:185], v[52:53], v[82:83], v[184:185]
	ds_read_b128 v[80:83], v186 offset:5440
	s_waitcnt lgkmcnt(8)
	v_pk_fma_f32 v[138:139], v[54:55], v[8:9], v[138:139]
	v_pk_fma_f32 v[184:185], v[56:57], v[10:11], v[184:185]
	ds_read_b128 v[8:11], v186 offset:5456
	s_waitcnt lgkmcnt(8)
	v_pk_fma_f32 v[138:139], v[58:59], v[12:13], v[138:139]
	ds_read_b128 v[12:15], v186 offset:5472
	v_add_f32_e32 v187, v138, v139
	v_add_f32_e32 v30, v184, v185
	v_add_f32_e32 v60, v187, v30
	v_cndmask_b32_e64 v84, 0, 1.0, vcc
	v_cvt_pk_bf16_f32 v30, v60, v60
	ds_write_b16 v29, v30 offset:2592
	s_waitcnt lgkmcnt(9)
	v_pk_fma_f32 v[138:139], v[42:43], v[16:17], v[84:85]
	v_cmp_eq_u32_e32 vcc, 20, v88
	v_pk_mul_f32 v[184:185], v[44:45], v[18:19]
	ds_read_b128 v[16:19], v186 offset:5488
	s_waitcnt lgkmcnt(9)
	v_pk_fma_f32 v[138:139], v[46:47], v[20:21], v[138:139]
	v_pk_fma_f32 v[184:185], v[48:49], v[22:23], v[184:185]
	ds_read_b128 v[20:23], v186 offset:5504
	s_waitcnt lgkmcnt(9)
	v_pk_fma_f32 v[138:139], v[50:51], v[24:25], v[138:139]
	v_pk_fma_f32 v[184:185], v[52:53], v[26:27], v[184:185]
	ds_read_b128 v[24:27], v186 offset:5712
	s_waitcnt lgkmcnt(8)
	v_pk_fma_f32 v[138:139], v[54:55], v[32:33], v[138:139]
	v_pk_fma_f32 v[184:185], v[56:57], v[34:35], v[184:185]
	ds_read_b128 v[32:35], v186 offset:5728
	s_waitcnt lgkmcnt(8)
	v_pk_fma_f32 v[138:139], v[58:59], v[36:37], v[138:139]
	v_fmac_f32_e32 v184, v60, v38
	ds_read_b128 v[36:39], v186 offset:5744
	v_add_f32_e32 v187, v138, v139
	v_add_f32_e32 v30, v184, v185
	v_add_f32_e32 v61, v187, v30
	v_cndmask_b32_e64 v84, 0, 1.0, vcc
	v_cvt_pk_bf16_f32 v30, v61, v61
	ds_write_b16 v29, v30 offset:2736
	s_waitcnt lgkmcnt(9)
	v_pk_fma_f32 v[138:139], v[42:43], v[80:81], v[84:85]
	v_cmp_eq_u32_e32 vcc, 21, v88
	v_pk_mul_f32 v[184:185], v[44:45], v[82:83]
	ds_read_b128 v[80:83], v186 offset:5760
	s_waitcnt lgkmcnt(9)
	v_pk_fma_f32 v[138:139], v[46:47], v[8:9], v[138:139]
	v_pk_fma_f32 v[184:185], v[48:49], v[10:11], v[184:185]
	ds_read_b128 v[8:11], v186 offset:5776
	s_waitcnt lgkmcnt(9)
	v_pk_fma_f32 v[138:139], v[50:51], v[12:13], v[138:139]
	v_pk_fma_f32 v[184:185], v[52:53], v[14:15], v[184:185]
	ds_read_b128 v[12:15], v186 offset:5792
	s_waitcnt lgkmcnt(8)
	v_pk_fma_f32 v[138:139], v[54:55], v[16:17], v[138:139]
	v_pk_fma_f32 v[184:185], v[56:57], v[18:19], v[184:185]
	ds_read_b128 v[16:19], v186 offset:5984
	s_waitcnt lgkmcnt(8)
	v_pk_fma_f32 v[138:139], v[58:59], v[20:21], v[138:139]
	v_pk_fma_f32 v[184:185], v[60:61], v[22:23], v[184:185]
	ds_read_b128 v[20:23], v186 offset:6000
	v_add_f32_e32 v187, v138, v139
	v_add_f32_e32 v30, v184, v185
	v_add_f32_e32 v62, v187, v30
	v_cndmask_b32_e64 v84, 0, 1.0, vcc
	v_cvt_pk_bf16_f32 v30, v62, v62
	ds_write_b16 v29, v30 offset:2880
	s_waitcnt lgkmcnt(9)
	v_pk_fma_f32 v[138:139], v[42:43], v[24:25], v[84:85]
	v_cmp_eq_u32_e32 vcc, 22, v88
	v_pk_mul_f32 v[184:185], v[44:45], v[26:27]
	ds_read_b128 v[24:27], v186 offset:6016
	s_waitcnt lgkmcnt(9)
	v_pk_fma_f32 v[138:139], v[46:47], v[32:33], v[138:139]
	v_pk_fma_f32 v[184:185], v[48:49], v[34:35], v[184:185]
	ds_read_b128 v[32:35], v186 offset:6032
	s_waitcnt lgkmcnt(9)
	v_pk_fma_f32 v[138:139], v[50:51], v[36:37], v[138:139]
	v_pk_fma_f32 v[184:185], v[52:53], v[38:39], v[184:185]
	ds_read_b128 v[36:39], v186 offset:6048
	s_waitcnt lgkmcnt(8)
	v_pk_fma_f32 v[138:139], v[54:55], v[80:81], v[138:139]
	v_pk_fma_f32 v[184:185], v[56:57], v[82:83], v[184:185]
	ds_read_b128 v[80:83], v186 offset:6064
	s_waitcnt lgkmcnt(8)
	v_pk_fma_f32 v[138:139], v[58:59], v[8:9], v[138:139]
	v_pk_fma_f32 v[184:185], v[60:61], v[10:11], v[184:185]
	ds_read_b128 v[8:11], v186 offset:6256
	s_waitcnt lgkmcnt(8)
	v_fmac_f32_e32 v138, v62, v12
	ds_read_b128 v[12:15], v186 offset:6272
	v_add_f32_e32 v187, v138, v139
	v_add_f32_e32 v30, v184, v185
	v_add_f32_e32 v63, v187, v30
	v_cndmask_b32_e64 v84, 0, 1.0, vcc
	v_cvt_pk_bf16_f32 v30, v63, v63
	ds_write_b16 v29, v30 offset:3024
	s_waitcnt lgkmcnt(9)
	v_pk_fma_f32 v[138:139], v[42:43], v[16:17], v[84:85]
	v_cmp_eq_u32_e32 vcc, 23, v88
	v_pk_mul_f32 v[184:185], v[44:45], v[18:19]
	ds_read_b128 v[16:19], v186 offset:6288
	s_waitcnt lgkmcnt(9)
	v_pk_fma_f32 v[138:139], v[46:47], v[20:21], v[138:139]
	v_pk_fma_f32 v[184:185], v[48:49], v[22:23], v[184:185]
	ds_read_b128 v[20:23], v186 offset:6304
	s_waitcnt lgkmcnt(8)
	v_pk_fma_f32 v[138:139], v[50:51], v[24:25], v[138:139]
	v_pk_fma_f32 v[184:185], v[52:53], v[26:27], v[184:185]
	ds_read_b128 v[24:27], v186 offset:6320
	s_waitcnt lgkmcnt(8)
	v_pk_fma_f32 v[138:139], v[54:55], v[32:33], v[138:139]
	v_pk_fma_f32 v[184:185], v[56:57], v[34:35], v[184:185]
	ds_read_b128 v[32:35], v186 offset:6336
	s_waitcnt lgkmcnt(8)
	v_pk_fma_f32 v[138:139], v[58:59], v[36:37], v[138:139]
	v_pk_fma_f32 v[184:185], v[60:61], v[38:39], v[184:185]
	ds_read_b128 v[36:39], v186 offset:6528
	s_waitcnt lgkmcnt(8)
; #define LAS __attribute__((address_space(3)))
; __device__ __forceinline__ bf16_t f2bf(float f) { unsigned u = __float_as_uint(f); u += 0x7FFFu + ((u >> 16) & 1u); return (bf16_t)(u >> 16); }
; __device__ __forceinline__ void phase_rwkv_ra(const Ctx& c, int p, int l) {
;     ...
;         if (w == 0) {
;             float M[64];
; #pragma unroll
;             for (int tt = 0; tt < 64; ++tt) {
;                 float a4[4] = {(lane == tt) ? 1.f : 0.f, 0.f, 0.f, 0.f};
; #pragma unroll
;                 for (int p4 = 0; p4 < (tt + 3) / 4; ++p4) {
;                     const f32x4 nv = *(const LAS f32x4*)(NfT + tt * 68 + 4 * p4);
; #pragma unroll
;                     for (int e = 0; e < 4; ++e) if (4 * p4 + e < tt) a4[e] += M[4 * p4 + e] * nv[e];
;                 }
;                 const float a = (a4[0] + a4[1]) + (a4[2] + a4[3]);
;                 M[tt] = a;
;                 MinvT[tt * RS + lane] = f2bf(a);
;             }
	v_pk_fma_f32 v[138:139], v[62:63], v[80:81], v[138:139]
	ds_read_b128 v[80:83], v186 offset:6544
	v_add_f32_e32 v187, v138, v139
	v_add_f32_e32 v30, v184, v185
	v_add_f32_e32 v64, v187, v30
	v_cndmask_b32_e64 v84, 0, 1.0, vcc
	v_cvt_pk_bf16_f32 v30, v64, v64
	ds_write_b16 v29, v30 offset:3168
	s_waitcnt lgkmcnt(9)
	v_pk_fma_f32 v[138:139], v[42:43], v[8:9], v[84:85]
	v_cmp_eq_u32_e32 vcc, 24, v88
	v_pk_mul_f32 v[184:185], v[44:45], v[10:11]
	ds_read_b128 v[8:11], v186 offset:6560
	s_waitcnt lgkmcnt(9)
	v_pk_fma_f32 v[138:139], v[46:47], v[12:13], v[138:139]
	v_pk_fma_f32 v[184:185], v[48:49], v[14:15], v[184:185]
	ds_read_b128 v[12:15], v186 offset:6576
	s_waitcnt lgkmcnt(8)
	v_pk_fma_f32 v[138:139], v[50:51], v[16:17], v[138:139]
	v_pk_fma_f32 v[184:185], v[52:53], v[18:19], v[184:185]
	ds_read_b128 v[16:19], v186 offset:6592
	s_waitcnt lgkmcnt(8)
	v_pk_fma_f32 v[138:139], v[54:55], v[20:21], v[138:139]
	v_pk_fma_f32 v[184:185], v[56:57], v[22:23], v[184:185]
	ds_read_b128 v[20:23], v186 offset:6608
	s_waitcnt lgkmcnt(8)
	v_pk_fma_f32 v[138:139], v[58:59], v[24:25], v[138:139]
	v_pk_fma_f32 v[184:185], v[60:61], v[26:27], v[184:185]
	ds_read_b128 v[24:27], v186 offset:6800
	s_waitcnt lgkmcnt(8)
	v_pk_fma_f32 v[138:139], v[62:63], v[32:33], v[138:139]
	v_fmac_f32_e32 v184, v64, v34
	ds_read_b128 v[32:35], v186 offset:6816
	v_add_f32_e32 v187, v138, v139
	v_add_f32_e32 v30, v184, v185
	v_add_f32_e32 v65, v187, v30
	v_cndmask_b32_e64 v84, 0, 1.0, vcc
	v_cvt_pk_bf16_f32 v30, v65, v65
	ds_write_b16 v29, v30 offset:3312
	s_waitcnt lgkmcnt(9)
	v_pk_fma_f32 v[138:139], v[42:43], v[36:37], v[84:85]
	v_cmp_eq_u32_e32 vcc, 25, v88
	v_pk_mul_f32 v[184:185], v[44:45], v[38:39]
	ds_read_b128 v[36:39], v186 offset:6832
	s_waitcnt lgkmcnt(9)
	v_pk_fma_f32 v[138:139], v[46:47], v[80:81], v[138:139]
	v_pk_fma_f32 v[184:185], v[48:49], v[82:83], v[184:185]
	ds_read_b128 v[80:83], v186 offset:6848
	s_waitcnt lgkmcnt(8)
	v_pk_fma_f32 v[138:139], v[50:51], v[8:9], v[138:139]
	v_pk_fma_f32 v[184:185], v[52:53], v[10:11], v[184:185]
	ds_read_b128 v[8:11], v186 offset:6864
	s_waitcnt lgkmcnt(8)
	v_pk_fma_f32 v[138:139], v[54:55], v[12:13], v[138:139]
	v_pk_fma_f32 v[184:185], v[56:57], v[14:15], v[184:185]
	ds_read_b128 v[12:15], v186 offset:6880
	s_waitcnt lgkmcnt(8)
	v_pk_fma_f32 v[138:139], v[58:59], v[16:17], v[138:139]
	v_pk_fma_f32 v[184:185], v[60:61], v[18:19], v[184:185]
	ds_read_b128 v[16:19], v186 offset:6896
	s_waitcnt lgkmcnt(8)
	v_pk_fma_f32 v[138:139], v[62:63], v[20:21], v[138:139]
	v_pk_fma_f32 v[184:185], v[64:65], v[22:23], v[184:185]
	ds_read_b128 v[20:23], v186 offset:7072
	v_add_f32_e32 v187, v138, v139
	v_add_f32_e32 v30, v184, v185
	v_add_f32_e32 v66, v187, v30
	v_cndmask_b32_e64 v84, 0, 1.0, vcc
	v_cvt_pk_bf16_f32 v30, v66, v66
	ds_write_b16 v29, v30 offset:3456
	s_waitcnt lgkmcnt(9)
	v_pk_fma_f32 v[138:139], v[42:43], v[24:25], v[84:85]
	v_cmp_eq_u32_e32 vcc, 26, v88
	v_pk_mul_f32 v[184:185], v[44:45], v[26:27]
	ds_read_b128 v[24:27], v186 offset:7088
	s_waitcnt lgkmcnt(9)
	v_pk_fma_f32 v[138:139], v[46:47], v[32:33], v[138:139]
	v_pk_fma_f32 v[184:185], v[48:49], v[34:35], v[184:185]
	ds_read_b128 v[32:35], v186 offset:7104
	s_waitcnt lgkmcnt(8)
	v_pk_fma_f32 v[138:139], v[50:51], v[36:37], v[138:139]
	v_pk_fma_f32 v[184:185], v[52:53], v[38:39], v[184:185]
	ds_read_b128 v[36:39], v186 offset:7120
	s_waitcnt lgkmcnt(8)
	v_pk_fma_f32 v[138:139], v[54:55], v[80:81], v[138:139]
	v_pk_fma_f32 v[184:185], v[56:57], v[82:83], v[184:185]
	ds_read_b128 v[80:83], v186 offset:7136
	s_waitcnt lgkmcnt(8)
	v_pk_fma_f32 v[138:139], v[58:59], v[8:9], v[138:139]
	v_pk_fma_f32 v[184:185], v[60:61], v[10:11], v[184:185]
	ds_read_b128 v[8:11], v186 offset:7152
	s_waitcnt lgkmcnt(8)
	v_pk_fma_f32 v[138:139], v[62:63], v[12:13], v[138:139]
	v_pk_fma_f32 v[184:185], v[64:65], v[14:15], v[184:185]
	ds_read_b128 v[12:15], v186 offset:7168
	s_waitcnt lgkmcnt(8)
	v_fmac_f32_e32 v138, v66, v16
	ds_read_b128 v[16:19], v186 offset:7344
	v_add_f32_e32 v187, v138, v139
	v_add_f32_e32 v30, v184, v185
	v_add_f32_e32 v67, v187, v30
	v_cndmask_b32_e64 v84, 0, 1.0, vcc
	v_cvt_pk_bf16_f32 v30, v67, v67
	ds_write_b16 v29, v30 offset:3600
	s_waitcnt lgkmcnt(9)
	v_pk_fma_f32 v[138:139], v[42:43], v[20:21], v[84:85]
	v_cmp_eq_u32_e32 vcc, 27, v88
	v_pk_mul_f32 v[184:185], v[44:45], v[22:23]
	ds_read_b128 v[20:23], v186 offset:7360
	s_waitcnt lgkmcnt(8)
	v_pk_fma_f32 v[138:139], v[46:47], v[24:25], v[138:139]
	v_pk_fma_f32 v[184:185], v[48:49], v[26:27], v[184:185]
	ds_read_b128 v[24:27], v186 offset:7376
	s_waitcnt lgkmcnt(8)
	v_pk_fma_f32 v[138:139], v[50:51], v[32:33], v[138:139]
	v_pk_fma_f32 v[184:185], v[52:53], v[34:35], v[184:185]
	ds_read_b128 v[32:35], v186 offset:7392
	s_waitcnt lgkmcnt(8)
	v_pk_fma_f32 v[138:139], v[54:55], v[36:37], v[138:139]
	v_pk_fma_f32 v[184:185], v[56:57], v[38:39], v[184:185]
	ds_read_b128 v[36:39], v186 offset:7408
	s_waitcnt lgkmcnt(8)
	v_pk_fma_f32 v[138:139], v[58:59], v[80:81], v[138:139]
	v_pk_fma_f32 v[184:185], v[60:61], v[82:83], v[184:185]
	ds_read_b128 v[80:83], v186 offset:7424
	s_waitcnt lgkmcnt(8)
	v_pk_fma_f32 v[138:139], v[62:63], v[8:9], v[138:139]
	v_pk_fma_f32 v[184:185], v[64:65], v[10:11], v[184:185]
	ds_read_b128 v[8:11], v186 offset:7440
	s_waitcnt lgkmcnt(8)
	v_pk_fma_f32 v[138:139], v[66:67], v[12:13], v[138:139]
	ds_read_b128 v[12:15], v186 offset:7616
	v_add_f32_e32 v187, v138, v139
	v_add_f32_e32 v30, v184, v185
	v_add_f32_e32 v68, v187, v30
	v_cndmask_b32_e64 v84, 0, 1.0, vcc
	v_cvt_pk_bf16_f32 v30, v68, v68
	ds_write_b16 v29, v30 offset:3744
	s_waitcnt lgkmcnt(9)
; #define LAS __attribute__((address_space(3)))
; __device__ __forceinline__ bf16_t f2bf(float f) { unsigned u = __float_as_uint(f); u += 0x7FFFu + ((u >> 16) & 1u); return (bf16_t)(u >> 16); }
; __device__ __forceinline__ void phase_rwkv_ra(const Ctx& c, int p, int l) {
;     ...
;         if (w == 0) {
;             float M[64];
; #pragma unroll
;             for (int tt = 0; tt < 64; ++tt) {
;                 float a4[4] = {(lane == tt) ? 1.f : 0.f, 0.f, 0.f, 0.f};
; #pragma unroll
;                 for (int p4 = 0; p4 < (tt + 3) / 4; ++p4) {
;                     const f32x4 nv = *(const LAS f32x4*)(NfT + tt * 68 + 4 * p4);
; #pragma unroll
;                     for (int e = 0; e < 4; ++e) if (4 * p4 + e < tt) a4[e] += M[4 * p4 + e] * nv[e];
;                 }
;                 const float a = (a4[0] + a4[1]) + (a4[2] + a4[3]);
;                 M[tt] = a;
;                 MinvT[tt * RS + lane] = f2bf(a);
;             }
	v_pk_fma_f32 v[138:139], v[42:43], v[16:17], v[84:85]
	v_cmp_eq_u32_e32 vcc, 28, v88
	v_pk_mul_f32 v[184:185], v[44:45], v[18:19]
	ds_read_b128 v[16:19], v186 offset:7632
	s_waitcnt lgkmcnt(8)
	v_pk_fma_f32 v[138:139], v[46:47], v[20:21], v[138:139]
	v_pk_fma_f32 v[184:185], v[48:49], v[22:23], v[184:185]
	ds_read_b128 v[20:23], v186 offset:7648
	s_waitcnt lgkmcnt(8)
	v_pk_fma_f32 v[138:139], v[50:51], v[24:25], v[138:139]
	v_pk_fma_f32 v[184:185], v[52:53], v[26:27], v[184:185]
	ds_read_b128 v[24:27], v186 offset:7664
	s_waitcnt lgkmcnt(8)
	v_pk_fma_f32 v[138:139], v[54:55], v[32:33], v[138:139]
	v_pk_fma_f32 v[184:185], v[56:57], v[34:35], v[184:185]
	ds_read_b128 v[32:35], v186 offset:7680
	s_waitcnt lgkmcnt(8)
	v_pk_fma_f32 v[138:139], v[58:59], v[36:37], v[138:139]
	v_pk_fma_f32 v[184:185], v[60:61], v[38:39], v[184:185]
	ds_read_b128 v[36:39], v186 offset:7696
	s_waitcnt lgkmcnt(8)
	v_pk_fma_f32 v[138:139], v[62:63], v[80:81], v[138:139]
	v_pk_fma_f32 v[184:185], v[64:65], v[82:83], v[184:185]
	ds_read_b128 v[80:83], v186 offset:7712
	s_waitcnt lgkmcnt(8)
	v_pk_fma_f32 v[138:139], v[66:67], v[8:9], v[138:139]
	v_fmac_f32_e32 v184, v68, v10
	ds_read_b128 v[8:11], v186 offset:7888
	v_add_f32_e32 v187, v138, v139
	v_add_f32_e32 v30, v184, v185
	v_add_f32_e32 v69, v187, v30
	v_cndmask_b32_e64 v84, 0, 1.0, vcc
	v_cvt_pk_bf16_f32 v30, v69, v69
	ds_write_b16 v29, v30 offset:3888
	s_waitcnt lgkmcnt(9)
	v_pk_fma_f32 v[138:139], v[42:43], v[12:13], v[84:85]
	v_cmp_eq_u32_e32 vcc, 29, v88
	v_pk_mul_f32 v[184:185], v[44:45], v[14:15]
	ds_read_b128 v[12:15], v186 offset:7904
	s_waitcnt lgkmcnt(8)
	v_pk_fma_f32 v[138:139], v[46:47], v[16:17], v[138:139]
	v_pk_fma_f32 v[184:185], v[48:49], v[18:19], v[184:185]
	ds_read_b128 v[16:19], v186 offset:7920
	s_waitcnt lgkmcnt(8)
	v_pk_fma_f32 v[138:139], v[50:51], v[20:21], v[138:139]
	v_pk_fma_f32 v[184:185], v[52:53], v[22:23], v[184:185]
	ds_read_b128 v[20:23], v186 offset:7936
	s_waitcnt lgkmcnt(8)
	v_pk_fma_f32 v[138:139], v[54:55], v[24:25], v[138:139]
	v_pk_fma_f32 v[184:185], v[56:57], v[26:27], v[184:185]
	ds_read_b128 v[24:27], v186 offset:7952
	s_waitcnt lgkmcnt(8)
	v_pk_fma_f32 v[138:139], v[58:59], v[32:33], v[138:139]
	v_pk_fma_f32 v[184:185], v[60:61], v[34:35], v[184:185]
	ds_read_b128 v[32:35], v186 offset:7968
	s_waitcnt lgkmcnt(8)
	v_pk_fma_f32 v[138:139], v[62:63], v[36:37], v[138:139]
	v_pk_fma_f32 v[184:185], v[64:65], v[38:39], v[184:185]
	ds_read_b128 v[36:39], v186 offset:7984
	s_waitcnt lgkmcnt(8)
	v_pk_fma_f32 v[138:139], v[66:67], v[80:81], v[138:139]
	v_pk_fma_f32 v[184:185], v[68:69], v[82:83], v[184:185]
	ds_read_b128 v[80:83], v186 offset:8000
	v_add_f32_e32 v187, v138, v139
	v_add_f32_e32 v30, v184, v185
	v_add_f32_e32 v70, v187, v30
	v_cndmask_b32_e64 v84, 0, 1.0, vcc
	v_cvt_pk_bf16_f32 v30, v70, v70
	ds_write_b16 v29, v30 offset:4032
	s_waitcnt lgkmcnt(9)
	v_pk_fma_f32 v[138:139], v[42:43], v[8:9], v[84:85]
	v_cmp_eq_u32_e32 vcc, 30, v88
	v_pk_mul_f32 v[184:185], v[44:45], v[10:11]
	ds_read_b128 v[8:11], v186 offset:8160
	s_waitcnt lgkmcnt(8)
	v_pk_fma_f32 v[138:139], v[46:47], v[12:13], v[138:139]
	v_pk_fma_f32 v[184:185], v[48:49], v[14:15], v[184:185]
	ds_read_b128 v[12:15], v186 offset:8176
	s_waitcnt lgkmcnt(8)
	v_pk_fma_f32 v[138:139], v[50:51], v[16:17], v[138:139]
	v_pk_fma_f32 v[184:185], v[52:53], v[18:19], v[184:185]
	ds_read_b128 v[16:19], v186 offset:8192
	s_waitcnt lgkmcnt(8)
	v_pk_fma_f32 v[138:139], v[54:55], v[20:21], v[138:139]
	v_pk_fma_f32 v[184:185], v[56:57], v[22:23], v[184:185]
	ds_read_b128 v[20:23], v186 offset:8208
	s_waitcnt lgkmcnt(8)
	v_pk_fma_f32 v[138:139], v[58:59], v[24:25], v[138:139]
	v_pk_fma_f32 v[184:185], v[60:61], v[26:27], v[184:185]
	ds_read_b128 v[24:27], v186 offset:8224
	s_waitcnt lgkmcnt(8)
	v_pk_fma_f32 v[138:139], v[62:63], v[32:33], v[138:139]
	v_pk_fma_f32 v[184:185], v[64:65], v[34:35], v[184:185]
	ds_read_b128 v[32:35], v186 offset:8240
	s_waitcnt lgkmcnt(8)
	v_pk_fma_f32 v[138:139], v[66:67], v[36:37], v[138:139]
	v_pk_fma_f32 v[184:185], v[68:69], v[38:39], v[184:185]
	ds_read_b128 v[36:39], v186 offset:8256
	s_waitcnt lgkmcnt(8)
	v_fmac_f32_e32 v138, v70, v80
	ds_read_b128 v[80:83], v186 offset:8272
	v_add_f32_e32 v187, v138, v139
	v_add_f32_e32 v30, v184, v185
	v_add_f32_e32 v71, v187, v30
	v_cndmask_b32_e64 v84, 0, 1.0, vcc
	v_cvt_pk_bf16_f32 v30, v71, v71
	ds_write_b16 v29, v30 offset:4176
	s_waitcnt lgkmcnt(8)
	v_pk_fma_f32 v[138:139], v[42:43], v[8:9], v[84:85]
	v_cmp_eq_u32_e32 vcc, 31, v88
	v_pk_mul_f32 v[184:185], v[44:45], v[10:11]
	ds_read_b128 v[8:11], v186 offset:8432
	s_waitcnt lgkmcnt(8)
	v_pk_fma_f32 v[138:139], v[46:47], v[12:13], v[138:139]
	v_pk_fma_f32 v[184:185], v[48:49], v[14:15], v[184:185]
	ds_read_b128 v[12:15], v186 offset:8448
	s_waitcnt lgkmcnt(8)
	v_pk_fma_f32 v[138:139], v[50:51], v[16:17], v[138:139]
	v_pk_fma_f32 v[184:185], v[52:53], v[18:19], v[184:185]
	ds_read_b128 v[16:19], v186 offset:8464
	s_waitcnt lgkmcnt(8)
	v_pk_fma_f32 v[138:139], v[54:55], v[20:21], v[138:139]
	v_pk_fma_f32 v[184:185], v[56:57], v[22:23], v[184:185]
	ds_read_b128 v[20:23], v186 offset:8480
	s_waitcnt lgkmcnt(8)
	v_pk_fma_f32 v[138:139], v[58:59], v[24:25], v[138:139]
	v_pk_fma_f32 v[184:185], v[60:61], v[26:27], v[184:185]
	ds_read_b128 v[24:27], v186 offset:8496
	s_waitcnt lgkmcnt(8)
	v_pk_fma_f32 v[138:139], v[62:63], v[32:33], v[138:139]
	v_pk_fma_f32 v[184:185], v[64:65], v[34:35], v[184:185]
	ds_read_b128 v[32:35], v186 offset:8512
	s_waitcnt lgkmcnt(8)
	v_pk_fma_f32 v[138:139], v[66:67], v[36:37], v[138:139]
	v_pk_fma_f32 v[184:185], v[68:69], v[38:39], v[184:185]
	ds_read_b128 v[36:39], v186 offset:8528
	s_waitcnt lgkmcnt(8)
; #define LAS __attribute__((address_space(3)))
; __device__ __forceinline__ bf16_t f2bf(float f) { unsigned u = __float_as_uint(f); u += 0x7FFFu + ((u >> 16) & 1u); return (bf16_t)(u >> 16); }
; __device__ __forceinline__ void phase_rwkv_ra(const Ctx& c, int p, int l) {
;     ...
;         if (w == 0) {
;             float M[64];
; #pragma unroll
;             for (int tt = 0; tt < 64; ++tt) {
;                 float a4[4] = {(lane == tt) ? 1.f : 0.f, 0.f, 0.f, 0.f};
; #pragma unroll
;                 for (int p4 = 0; p4 < (tt + 3) / 4; ++p4) {
;                     const f32x4 nv = *(const LAS f32x4*)(NfT + tt * 68 + 4 * p4);
; #pragma unroll
;                     for (int e = 0; e < 4; ++e) if (4 * p4 + e < tt) a4[e] += M[4 * p4 + e] * nv[e];
;                 }
;                 const float a = (a4[0] + a4[1]) + (a4[2] + a4[3]);
;                 M[tt] = a;
;                 MinvT[tt * RS + lane] = f2bf(a);
;             }
	v_pk_fma_f32 v[138:139], v[70:71], v[80:81], v[138:139]
	ds_read_b128 v[80:83], v186 offset:8544
	v_add_f32_e32 v187, v138, v139
	v_add_f32_e32 v30, v184, v185
	v_add_f32_e32 v72, v187, v30
	v_cndmask_b32_e64 v84, 0, 1.0, vcc
	v_cvt_pk_bf16_f32 v30, v72, v72
	ds_write_b16 v29, v30 offset:4320
	s_waitcnt lgkmcnt(8)
	v_pk_fma_f32 v[138:139], v[42:43], v[8:9], v[84:85]
	v_cmp_eq_u32_e32 vcc, 32, v88
	v_pk_mul_f32 v[184:185], v[44:45], v[10:11]
	ds_read_b128 v[8:11], v186 offset:8704
	s_waitcnt lgkmcnt(8)
	v_pk_fma_f32 v[138:139], v[46:47], v[12:13], v[138:139]
	v_pk_fma_f32 v[184:185], v[48:49], v[14:15], v[184:185]
	ds_read_b128 v[12:15], v186 offset:8720
	s_waitcnt lgkmcnt(8)
	v_pk_fma_f32 v[138:139], v[50:51], v[16:17], v[138:139]
	v_pk_fma_f32 v[184:185], v[52:53], v[18:19], v[184:185]
	ds_read_b128 v[16:19], v186 offset:8736
	s_waitcnt lgkmcnt(8)
	v_pk_fma_f32 v[138:139], v[54:55], v[20:21], v[138:139]
	v_pk_fma_f32 v[184:185], v[56:57], v[22:23], v[184:185]
	ds_read_b128 v[20:23], v186 offset:8752
	s_waitcnt lgkmcnt(8)
	v_pk_fma_f32 v[138:139], v[58:59], v[24:25], v[138:139]
	v_pk_fma_f32 v[184:185], v[60:61], v[26:27], v[184:185]
	ds_read_b128 v[24:27], v186 offset:8768
	s_waitcnt lgkmcnt(8)
	v_pk_fma_f32 v[138:139], v[62:63], v[32:33], v[138:139]
	v_pk_fma_f32 v[184:185], v[64:65], v[34:35], v[184:185]
	ds_read_b128 v[32:35], v186 offset:8784
	s_waitcnt lgkmcnt(8)
	v_pk_fma_f32 v[138:139], v[66:67], v[36:37], v[138:139]
	v_pk_fma_f32 v[184:185], v[68:69], v[38:39], v[184:185]
	ds_read_b128 v[36:39], v186 offset:8800
	s_waitcnt lgkmcnt(8)
	v_pk_fma_f32 v[138:139], v[70:71], v[80:81], v[138:139]
	v_fmac_f32_e32 v184, v72, v82
	ds_read_b128 v[80:83], v186 offset:8816
	v_add_f32_e32 v187, v138, v139
	v_add_f32_e32 v30, v184, v185
	v_add_f32_e32 v73, v187, v30
	v_cndmask_b32_e64 v84, 0, 1.0, vcc
	v_cvt_pk_bf16_f32 v30, v73, v73
	ds_write_b16 v29, v30 offset:4464
	s_waitcnt lgkmcnt(8)
	v_pk_fma_f32 v[138:139], v[42:43], v[8:9], v[84:85]
	v_cmp_eq_u32_e32 vcc, 33, v88
	v_pk_mul_f32 v[184:185], v[44:45], v[10:11]
	ds_read_b128 v[8:11], v186 offset:8976
	s_waitcnt lgkmcnt(8)
	v_pk_fma_f32 v[138:139], v[46:47], v[12:13], v[138:139]
	v_pk_fma_f32 v[184:185], v[48:49], v[14:15], v[184:185]
	ds_read_b128 v[12:15], v186 offset:8992
	s_waitcnt lgkmcnt(8)
	v_pk_fma_f32 v[138:139], v[50:51], v[16:17], v[138:139]
	v_pk_fma_f32 v[184:185], v[52:53], v[18:19], v[184:185]
	ds_read_b128 v[16:19], v186 offset:9008
	s_waitcnt lgkmcnt(8)
	v_pk_fma_f32 v[138:139], v[54:55], v[20:21], v[138:139]
	v_pk_fma_f32 v[184:185], v[56:57], v[22:23], v[184:185]
	ds_read_b128 v[20:23], v186 offset:9024
	s_waitcnt lgkmcnt(8)
	v_pk_fma_f32 v[138:139], v[58:59], v[24:25], v[138:139]
	v_pk_fma_f32 v[184:185], v[60:61], v[26:27], v[184:185]
	ds_read_b128 v[24:27], v186 offset:9040
	s_waitcnt lgkmcnt(8)
	v_pk_fma_f32 v[138:139], v[62:63], v[32:33], v[138:139]
	v_pk_fma_f32 v[184:185], v[64:65], v[34:35], v[184:185]
	ds_read_b128 v[32:35], v186 offset:9056
	s_waitcnt lgkmcnt(8)
	v_pk_fma_f32 v[138:139], v[66:67], v[36:37], v[138:139]
	v_pk_fma_f32 v[184:185], v[68:69], v[38:39], v[184:185]
	ds_read_b128 v[36:39], v186 offset:9072
	s_waitcnt lgkmcnt(8)
	v_pk_fma_f32 v[138:139], v[70:71], v[80:81], v[138:139]
	v_pk_fma_f32 v[184:185], v[72:73], v[82:83], v[184:185]
	ds_read_b128 v[80:83], v186 offset:9088
	v_add_f32_e32 v187, v138, v139
	v_add_f32_e32 v30, v184, v185
	v_add_f32_e32 v144, v187, v30
	v_cndmask_b32_e64 v84, 0, 1.0, vcc
	v_cvt_pk_bf16_f32 v30, v144, v144
	ds_write_b16 v29, v30 offset:4608
	s_waitcnt lgkmcnt(8)
	v_pk_fma_f32 v[138:139], v[42:43], v[8:9], v[84:85]
	v_cmp_eq_u32_e32 vcc, 34, v88
	v_pk_mul_f32 v[184:185], v[44:45], v[10:11]
	ds_read_b128 v[8:11], v186 offset:9104
	s_waitcnt lgkmcnt(8)
	v_pk_fma_f32 v[138:139], v[46:47], v[12:13], v[138:139]
	v_pk_fma_f32 v[184:185], v[48:49], v[14:15], v[184:185]
	ds_read_b128 v[12:15], v186 offset:9248
	s_waitcnt lgkmcnt(8)
	v_pk_fma_f32 v[138:139], v[50:51], v[16:17], v[138:139]
	v_pk_fma_f32 v[184:185], v[52:53], v[18:19], v[184:185]
	ds_read_b128 v[16:19], v186 offset:9264
	s_waitcnt lgkmcnt(8)
	v_pk_fma_f32 v[138:139], v[54:55], v[20:21], v[138:139]
	v_pk_fma_f32 v[184:185], v[56:57], v[22:23], v[184:185]
	ds_read_b128 v[20:23], v186 offset:9280
	s_waitcnt lgkmcnt(8)
	v_pk_fma_f32 v[138:139], v[58:59], v[24:25], v[138:139]
	v_pk_fma_f32 v[184:185], v[60:61], v[26:27], v[184:185]
	ds_read_b128 v[24:27], v186 offset:9296
	s_waitcnt lgkmcnt(8)
	v_pk_fma_f32 v[138:139], v[62:63], v[32:33], v[138:139]
	v_pk_fma_f32 v[184:185], v[64:65], v[34:35], v[184:185]
	ds_read_b128 v[32:35], v186 offset:9312
	s_waitcnt lgkmcnt(8)
	v_pk_fma_f32 v[138:139], v[66:67], v[36:37], v[138:139]
	v_pk_fma_f32 v[184:185], v[68:69], v[38:39], v[184:185]
	ds_read_b128 v[36:39], v186 offset:9328
	s_waitcnt lgkmcnt(8)
	v_pk_fma_f32 v[138:139], v[70:71], v[80:81], v[138:139]
	v_pk_fma_f32 v[184:185], v[72:73], v[82:83], v[184:185]
	ds_read_b128 v[80:83], v186 offset:9344
	s_waitcnt lgkmcnt(7)
	v_fmac_f32_e32 v138, v144, v8
	ds_read_b128 v[8:11], v186 offset:9360
	v_add_f32_e32 v187, v138, v139
	v_add_f32_e32 v30, v184, v185
	v_add_f32_e32 v145, v187, v30
	v_cndmask_b32_e64 v84, 0, 1.0, vcc
	v_cvt_pk_bf16_f32 v30, v145, v145
	ds_write_b16 v29, v30 offset:4752
	s_waitcnt lgkmcnt(8)
	v_pk_fma_f32 v[138:139], v[42:43], v[12:13], v[84:85]
	v_cmp_eq_u32_e32 vcc, 35, v88
	v_pk_mul_f32 v[184:185], v[44:45], v[14:15]
	ds_read_b128 v[12:15], v186 offset:9376
	s_waitcnt lgkmcnt(8)
	v_pk_fma_f32 v[138:139], v[46:47], v[16:17], v[138:139]
	v_pk_fma_f32 v[184:185], v[48:49], v[18:19], v[184:185]
	ds_read_b128 v[16:19], v186 offset:9520
	s_waitcnt lgkmcnt(8)
; #define LAS __attribute__((address_space(3)))
; __device__ __forceinline__ bf16_t f2bf(float f) { unsigned u = __float_as_uint(f); u += 0x7FFFu + ((u >> 16) & 1u); return (bf16_t)(u >> 16); }
; __device__ __forceinline__ void phase_rwkv_ra(const Ctx& c, int p, int l) {
;     ...
;         if (w == 0) {
;             float M[64];
; #pragma unroll
;             for (int tt = 0; tt < 64; ++tt) {
;                 float a4[4] = {(lane == tt) ? 1.f : 0.f, 0.f, 0.f, 0.f};
; #pragma unroll
;                 for (int p4 = 0; p4 < (tt + 3) / 4; ++p4) {
;                     const f32x4 nv = *(const LAS f32x4*)(NfT + tt * 68 + 4 * p4);
; #pragma unroll
;                     for (int e = 0; e < 4; ++e) if (4 * p4 + e < tt) a4[e] += M[4 * p4 + e] * nv[e];
;                 }
;                 const float a = (a4[0] + a4[1]) + (a4[2] + a4[3]);
;                 M[tt] = a;
;                 MinvT[tt * RS + lane] = f2bf(a);
;             }
	v_pk_fma_f32 v[138:139], v[50:51], v[20:21], v[138:139]
	v_pk_fma_f32 v[184:185], v[52:53], v[22:23], v[184:185]
	ds_read_b128 v[20:23], v186 offset:9536
	s_waitcnt lgkmcnt(8)
	v_pk_fma_f32 v[138:139], v[54:55], v[24:25], v[138:139]
	v_pk_fma_f32 v[184:185], v[56:57], v[26:27], v[184:185]
	ds_read_b128 v[24:27], v186 offset:9552
	s_waitcnt lgkmcnt(8)
	v_pk_fma_f32 v[138:139], v[58:59], v[32:33], v[138:139]
	v_pk_fma_f32 v[184:185], v[60:61], v[34:35], v[184:185]
	ds_read_b128 v[32:35], v186 offset:9568
	s_waitcnt lgkmcnt(8)
	v_pk_fma_f32 v[138:139], v[62:63], v[36:37], v[138:139]
	v_pk_fma_f32 v[184:185], v[64:65], v[38:39], v[184:185]
	ds_read_b128 v[36:39], v186 offset:9584
	s_waitcnt lgkmcnt(8)
	v_pk_fma_f32 v[138:139], v[66:67], v[80:81], v[138:139]
	v_pk_fma_f32 v[184:185], v[68:69], v[82:83], v[184:185]
	ds_read_b128 v[80:83], v186 offset:9600
	s_waitcnt lgkmcnt(8)
	v_pk_fma_f32 v[138:139], v[70:71], v[8:9], v[138:139]
	v_pk_fma_f32 v[184:185], v[72:73], v[10:11], v[184:185]
	ds_read_b128 v[8:11], v186 offset:9616
	s_waitcnt lgkmcnt(7)
	v_pk_fma_f32 v[138:139], v[144:145], v[12:13], v[138:139]
	ds_read_b128 v[12:15], v186 offset:9632
	v_add_f32_e32 v187, v138, v139
	v_add_f32_e32 v30, v184, v185
	v_add_f32_e32 v146, v187, v30
	v_cndmask_b32_e64 v84, 0, 1.0, vcc
	v_cvt_pk_bf16_f32 v30, v146, v146
	ds_write_b16 v29, v30 offset:4896
	s_waitcnt lgkmcnt(8)
	v_pk_fma_f32 v[138:139], v[42:43], v[16:17], v[84:85]
	v_cmp_eq_u32_e32 vcc, 36, v88
	v_pk_mul_f32 v[184:185], v[44:45], v[18:19]
	ds_read_b128 v[16:19], v186 offset:9648
	s_waitcnt lgkmcnt(8)
	v_pk_fma_f32 v[138:139], v[46:47], v[20:21], v[138:139]
	v_pk_fma_f32 v[184:185], v[48:49], v[22:23], v[184:185]
	ds_read_b128 v[20:23], v186 offset:9792
	s_waitcnt lgkmcnt(8)
	v_pk_fma_f32 v[138:139], v[50:51], v[24:25], v[138:139]
	v_pk_fma_f32 v[184:185], v[52:53], v[26:27], v[184:185]
	ds_read_b128 v[24:27], v186 offset:9808
	s_waitcnt lgkmcnt(8)
	v_pk_fma_f32 v[138:139], v[54:55], v[32:33], v[138:139]
	v_pk_fma_f32 v[184:185], v[56:57], v[34:35], v[184:185]
	ds_read_b128 v[32:35], v186 offset:9824
	s_waitcnt lgkmcnt(8)
	v_pk_fma_f32 v[138:139], v[58:59], v[36:37], v[138:139]
	v_pk_fma_f32 v[184:185], v[60:61], v[38:39], v[184:185]
	ds_read_b128 v[36:39], v186 offset:9840
	s_waitcnt lgkmcnt(8)
	v_pk_fma_f32 v[138:139], v[62:63], v[80:81], v[138:139]
	v_pk_fma_f32 v[184:185], v[64:65], v[82:83], v[184:185]
	ds_read_b128 v[80:83], v186 offset:9856
	s_waitcnt lgkmcnt(8)
	v_pk_fma_f32 v[138:139], v[66:67], v[8:9], v[138:139]
	v_pk_fma_f32 v[184:185], v[68:69], v[10:11], v[184:185]
	ds_read_b128 v[8:11], v186 offset:9872
	s_waitcnt lgkmcnt(8)
	v_pk_fma_f32 v[138:139], v[70:71], v[12:13], v[138:139]
	v_pk_fma_f32 v[184:185], v[72:73], v[14:15], v[184:185]
	ds_read_b128 v[12:15], v186 offset:9888
	s_waitcnt lgkmcnt(7)
	v_pk_fma_f32 v[138:139], v[144:145], v[16:17], v[138:139]
	v_fmac_f32_e32 v184, v146, v18
	ds_read_b128 v[16:19], v186 offset:9904
	v_add_f32_e32 v187, v138, v139
	v_add_f32_e32 v30, v184, v185
	v_add_f32_e32 v147, v187, v30
	v_cndmask_b32_e64 v84, 0, 1.0, vcc
	v_cvt_pk_bf16_f32 v30, v147, v147
	ds_write_b16 v29, v30 offset:5040
	s_waitcnt lgkmcnt(8)
	v_pk_fma_f32 v[138:139], v[42:43], v[20:21], v[84:85]
	v_cmp_eq_u32_e32 vcc, 37, v88
	v_pk_mul_f32 v[184:185], v[44:45], v[22:23]
	ds_read_b128 v[20:23], v186 offset:9920
	s_waitcnt lgkmcnt(8)
	v_pk_fma_f32 v[138:139], v[46:47], v[24:25], v[138:139]
	v_pk_fma_f32 v[184:185], v[48:49], v[26:27], v[184:185]
	ds_read_b128 v[24:27], v186 offset:10064
	s_waitcnt lgkmcnt(8)
	v_pk_fma_f32 v[138:139], v[50:51], v[32:33], v[138:139]
	v_pk_fma_f32 v[184:185], v[52:53], v[34:35], v[184:185]
	ds_read_b128 v[32:35], v186 offset:10080
	s_waitcnt lgkmcnt(8)
	v_pk_fma_f32 v[138:139], v[54:55], v[36:37], v[138:139]
	v_pk_fma_f32 v[184:185], v[56:57], v[38:39], v[184:185]
	ds_read_b128 v[36:39], v186 offset:10096
	s_waitcnt lgkmcnt(8)
	v_pk_fma_f32 v[138:139], v[58:59], v[80:81], v[138:139]
	v_pk_fma_f32 v[184:185], v[60:61], v[82:83], v[184:185]
	ds_read_b128 v[80:83], v186 offset:10112
	s_waitcnt lgkmcnt(8)
	v_pk_fma_f32 v[138:139], v[62:63], v[8:9], v[138:139]
	v_pk_fma_f32 v[184:185], v[64:65], v[10:11], v[184:185]
	ds_read_b128 v[8:11], v186 offset:10128
	s_waitcnt lgkmcnt(8)
	v_pk_fma_f32 v[138:139], v[66:67], v[12:13], v[138:139]
	v_pk_fma_f32 v[184:185], v[68:69], v[14:15], v[184:185]
	ds_read_b128 v[12:15], v186 offset:10144
	s_waitcnt lgkmcnt(8)
	v_pk_fma_f32 v[138:139], v[70:71], v[16:17], v[138:139]
	v_pk_fma_f32 v[184:185], v[72:73], v[18:19], v[184:185]
	ds_read_b128 v[16:19], v186 offset:10160
	s_waitcnt lgkmcnt(7)
	v_pk_fma_f32 v[138:139], v[144:145], v[20:21], v[138:139]
	v_pk_fma_f32 v[184:185], v[146:147], v[22:23], v[184:185]
	ds_read_b128 v[20:23], v186 offset:10176
	v_add_f32_e32 v187, v138, v139
	v_add_f32_e32 v30, v184, v185
	v_add_f32_e32 v148, v187, v30
	v_cndmask_b32_e64 v84, 0, 1.0, vcc
	v_cvt_pk_bf16_f32 v30, v148, v148
	ds_write_b16 v29, v30 offset:5184
	s_waitcnt lgkmcnt(8)
	v_pk_fma_f32 v[138:139], v[42:43], v[24:25], v[84:85]
	v_cmp_eq_u32_e32 vcc, 38, v88
	v_pk_mul_f32 v[184:185], v[44:45], v[26:27]
	ds_read_b128 v[24:27], v186 offset:10192
	s_waitcnt lgkmcnt(8)
	v_pk_fma_f32 v[138:139], v[46:47], v[32:33], v[138:139]
	v_pk_fma_f32 v[184:185], v[48:49], v[34:35], v[184:185]
	ds_read_b128 v[32:35], v186 offset:10208
	s_waitcnt lgkmcnt(8)
	v_pk_fma_f32 v[138:139], v[50:51], v[36:37], v[138:139]
	v_pk_fma_f32 v[184:185], v[52:53], v[38:39], v[184:185]
	ds_read_b128 v[36:39], v186 offset:10336
	s_waitcnt lgkmcnt(8)
	v_pk_fma_f32 v[138:139], v[54:55], v[80:81], v[138:139]
	v_pk_fma_f32 v[184:185], v[56:57], v[82:83], v[184:185]
	ds_read_b128 v[80:83], v186 offset:10352
	s_waitcnt lgkmcnt(8)
; #define LAS __attribute__((address_space(3)))
; __device__ __forceinline__ bf16_t f2bf(float f) { unsigned u = __float_as_uint(f); u += 0x7FFFu + ((u >> 16) & 1u); return (bf16_t)(u >> 16); }
; __device__ __forceinline__ void phase_rwkv_ra(const Ctx& c, int p, int l) {
;     ...
;         if (w == 0) {
;             float M[64];
; #pragma unroll
;             for (int tt = 0; tt < 64; ++tt) {
;                 float a4[4] = {(lane == tt) ? 1.f : 0.f, 0.f, 0.f, 0.f};
; #pragma unroll
;                 for (int p4 = 0; p4 < (tt + 3) / 4; ++p4) {
;                     const f32x4 nv = *(const LAS f32x4*)(NfT + tt * 68 + 4 * p4);
; #pragma unroll
;                     for (int e = 0; e < 4; ++e) if (4 * p4 + e < tt) a4[e] += M[4 * p4 + e] * nv[e];
;                 }
;                 const float a = (a4[0] + a4[1]) + (a4[2] + a4[3]);
;                 M[tt] = a;
;                 MinvT[tt * RS + lane] = f2bf(a);
;             }
	v_pk_fma_f32 v[138:139], v[58:59], v[8:9], v[138:139]
	v_pk_fma_f32 v[184:185], v[60:61], v[10:11], v[184:185]
	ds_read_b128 v[8:11], v186 offset:10368
	s_waitcnt lgkmcnt(8)
	v_pk_fma_f32 v[138:139], v[62:63], v[12:13], v[138:139]
	v_pk_fma_f32 v[184:185], v[64:65], v[14:15], v[184:185]
	ds_read_b128 v[12:15], v186 offset:10384
	s_waitcnt lgkmcnt(8)
	v_pk_fma_f32 v[138:139], v[66:67], v[16:17], v[138:139]
	v_pk_fma_f32 v[184:185], v[68:69], v[18:19], v[184:185]
	ds_read_b128 v[16:19], v186 offset:10400
	s_waitcnt lgkmcnt(8)
	v_pk_fma_f32 v[138:139], v[70:71], v[20:21], v[138:139]
	v_pk_fma_f32 v[184:185], v[72:73], v[22:23], v[184:185]
	ds_read_b128 v[20:23], v186 offset:10416
	s_waitcnt lgkmcnt(7)
	v_pk_fma_f32 v[138:139], v[144:145], v[24:25], v[138:139]
	v_pk_fma_f32 v[184:185], v[146:147], v[26:27], v[184:185]
	ds_read_b128 v[24:27], v186 offset:10432
	s_waitcnt lgkmcnt(7)
	v_fmac_f32_e32 v138, v148, v32
	ds_read_b128 v[32:35], v186 offset:10448
	v_add_f32_e32 v187, v138, v139
	v_add_f32_e32 v30, v184, v185
	v_add_f32_e32 v149, v187, v30
	v_cndmask_b32_e64 v84, 0, 1.0, vcc
	v_cvt_pk_bf16_f32 v30, v149, v149
	ds_write_b16 v29, v30 offset:5328
	s_waitcnt lgkmcnt(8)
	v_pk_fma_f32 v[138:139], v[42:43], v[36:37], v[84:85]
	v_cmp_eq_u32_e32 vcc, 39, v88
	v_pk_mul_f32 v[184:185], v[44:45], v[38:39]
	ds_read_b128 v[36:39], v186 offset:10464
	s_waitcnt lgkmcnt(8)
	v_pk_fma_f32 v[138:139], v[46:47], v[80:81], v[138:139]
	v_pk_fma_f32 v[184:185], v[48:49], v[82:83], v[184:185]
	ds_read_b128 v[80:83], v186 offset:10480
	s_waitcnt lgkmcnt(8)
	v_pk_fma_f32 v[138:139], v[50:51], v[8:9], v[138:139]
	v_pk_fma_f32 v[184:185], v[52:53], v[10:11], v[184:185]
	ds_read_b128 v[8:11], v186 offset:10608
	s_waitcnt lgkmcnt(8)
	v_pk_fma_f32 v[138:139], v[54:55], v[12:13], v[138:139]
	v_pk_fma_f32 v[184:185], v[56:57], v[14:15], v[184:185]
	ds_read_b128 v[12:15], v186 offset:10624
	s_waitcnt lgkmcnt(8)
	v_pk_fma_f32 v[138:139], v[58:59], v[16:17], v[138:139]
	v_pk_fma_f32 v[184:185], v[60:61], v[18:19], v[184:185]
	ds_read_b128 v[16:19], v186 offset:10640
	s_waitcnt lgkmcnt(8)
	v_pk_fma_f32 v[138:139], v[62:63], v[20:21], v[138:139]
	v_pk_fma_f32 v[184:185], v[64:65], v[22:23], v[184:185]
	ds_read_b128 v[20:23], v186 offset:10656
	s_waitcnt lgkmcnt(8)
	v_pk_fma_f32 v[138:139], v[66:67], v[24:25], v[138:139]
	v_pk_fma_f32 v[184:185], v[68:69], v[26:27], v[184:185]
	ds_read_b128 v[24:27], v186 offset:10672
	s_waitcnt lgkmcnt(8)
	v_pk_fma_f32 v[138:139], v[70:71], v[32:33], v[138:139]
	v_pk_fma_f32 v[184:185], v[72:73], v[34:35], v[184:185]
	ds_read_b128 v[32:35], v186 offset:10688
	s_waitcnt lgkmcnt(7)
	v_pk_fma_f32 v[138:139], v[144:145], v[36:37], v[138:139]
	v_pk_fma_f32 v[184:185], v[146:147], v[38:39], v[184:185]
	ds_read_b128 v[36:39], v186 offset:10704
	s_waitcnt lgkmcnt(7)
	v_pk_fma_f32 v[138:139], v[148:149], v[80:81], v[138:139]
	ds_read_b128 v[80:83], v186 offset:10720
	v_add_f32_e32 v187, v138, v139
	v_add_f32_e32 v30, v184, v185
	v_add_f32_e32 v150, v187, v30
	v_cndmask_b32_e64 v84, 0, 1.0, vcc
	v_cvt_pk_bf16_f32 v30, v150, v150
	ds_write_b16 v29, v30 offset:5472
	s_waitcnt lgkmcnt(8)
	v_pk_fma_f32 v[138:139], v[42:43], v[8:9], v[84:85]
	v_cmp_eq_u32_e32 vcc, 40, v88
	v_pk_mul_f32 v[184:185], v[44:45], v[10:11]
	ds_read_b128 v[8:11], v186 offset:10736
	s_waitcnt lgkmcnt(8)
	v_pk_fma_f32 v[138:139], v[46:47], v[12:13], v[138:139]
	v_pk_fma_f32 v[184:185], v[48:49], v[14:15], v[184:185]
	ds_read_b128 v[12:15], v186 offset:10752
	s_waitcnt lgkmcnt(8)
	v_pk_fma_f32 v[138:139], v[50:51], v[16:17], v[138:139]
	v_pk_fma_f32 v[184:185], v[52:53], v[18:19], v[184:185]
	ds_read_b128 v[16:19], v186 offset:10880
	s_waitcnt lgkmcnt(8)
	v_pk_fma_f32 v[138:139], v[54:55], v[20:21], v[138:139]
	v_pk_fma_f32 v[184:185], v[56:57], v[22:23], v[184:185]
	ds_read_b128 v[20:23], v186 offset:10896
	s_waitcnt lgkmcnt(8)
	v_pk_fma_f32 v[138:139], v[58:59], v[24:25], v[138:139]
	v_pk_fma_f32 v[184:185], v[60:61], v[26:27], v[184:185]
	ds_read_b128 v[24:27], v186 offset:10912
	s_waitcnt lgkmcnt(8)
	v_pk_fma_f32 v[138:139], v[62:63], v[32:33], v[138:139]
	v_pk_fma_f32 v[184:185], v[64:65], v[34:35], v[184:185]
	ds_read_b128 v[32:35], v186 offset:10928
	s_waitcnt lgkmcnt(8)
	v_pk_fma_f32 v[138:139], v[66:67], v[36:37], v[138:139]
	v_pk_fma_f32 v[184:185], v[68:69], v[38:39], v[184:185]
	ds_read_b128 v[36:39], v186 offset:10944
	s_waitcnt lgkmcnt(8)
	v_pk_fma_f32 v[138:139], v[70:71], v[80:81], v[138:139]
	v_pk_fma_f32 v[184:185], v[72:73], v[82:83], v[184:185]
	ds_read_b128 v[80:83], v186 offset:10960
	s_waitcnt lgkmcnt(7)
	v_pk_fma_f32 v[138:139], v[144:145], v[8:9], v[138:139]
	v_pk_fma_f32 v[184:185], v[146:147], v[10:11], v[184:185]
	ds_read_b128 v[8:11], v186 offset:10976
	s_waitcnt lgkmcnt(7)
	v_pk_fma_f32 v[138:139], v[148:149], v[12:13], v[138:139]
	v_fmac_f32_e32 v184, v150, v14
	ds_read_b128 v[12:15], v186 offset:10992
	v_add_f32_e32 v187, v138, v139
	v_add_f32_e32 v30, v184, v185
	v_add_f32_e32 v151, v187, v30
	v_cndmask_b32_e64 v84, 0, 1.0, vcc
	v_cvt_pk_bf16_f32 v30, v151, v151
	ds_write_b16 v29, v30 offset:5616
	s_waitcnt lgkmcnt(8)
	v_pk_fma_f32 v[138:139], v[42:43], v[16:17], v[84:85]
	v_cmp_eq_u32_e32 vcc, 41, v88
	v_pk_mul_f32 v[184:185], v[44:45], v[18:19]
	ds_read_b128 v[16:19], v186 offset:11008
	s_waitcnt lgkmcnt(8)
	v_pk_fma_f32 v[138:139], v[46:47], v[20:21], v[138:139]
	v_pk_fma_f32 v[184:185], v[48:49], v[22:23], v[184:185]
	ds_read_b128 v[20:23], v186 offset:11024
	s_waitcnt lgkmcnt(8)
	v_pk_fma_f32 v[138:139], v[50:51], v[24:25], v[138:139]
	v_pk_fma_f32 v[184:185], v[52:53], v[26:27], v[184:185]
	ds_read_b128 v[24:27], v186 offset:11152
	s_waitcnt lgkmcnt(8)
; #define LAS __attribute__((address_space(3)))
; __device__ __forceinline__ bf16_t f2bf(float f) { unsigned u = __float_as_uint(f); u += 0x7FFFu + ((u >> 16) & 1u); return (bf16_t)(u >> 16); }
; __device__ __forceinline__ void phase_rwkv_ra(const Ctx& c, int p, int l) {
;     ...
;         if (w == 0) {
;             float M[64];
; #pragma unroll
;             for (int tt = 0; tt < 64; ++tt) {
;                 float a4[4] = {(lane == tt) ? 1.f : 0.f, 0.f, 0.f, 0.f};
; #pragma unroll
;                 for (int p4 = 0; p4 < (tt + 3) / 4; ++p4) {
;                     const f32x4 nv = *(const LAS f32x4*)(NfT + tt * 68 + 4 * p4);
; #pragma unroll
;                     for (int e = 0; e < 4; ++e) if (4 * p4 + e < tt) a4[e] += M[4 * p4 + e] * nv[e];
;                 }
;                 const float a = (a4[0] + a4[1]) + (a4[2] + a4[3]);
;                 M[tt] = a;
;                 MinvT[tt * RS + lane] = f2bf(a);
;             }
	v_pk_fma_f32 v[138:139], v[54:55], v[32:33], v[138:139]
	v_pk_fma_f32 v[184:185], v[56:57], v[34:35], v[184:185]
	ds_read_b128 v[32:35], v186 offset:11168
	s_waitcnt lgkmcnt(8)
	v_pk_fma_f32 v[138:139], v[58:59], v[36:37], v[138:139]
	v_pk_fma_f32 v[184:185], v[60:61], v[38:39], v[184:185]
	ds_read_b128 v[36:39], v186 offset:11184
	s_waitcnt lgkmcnt(8)
	v_pk_fma_f32 v[138:139], v[62:63], v[80:81], v[138:139]
	v_pk_fma_f32 v[184:185], v[64:65], v[82:83], v[184:185]
	ds_read_b128 v[80:83], v186 offset:11200
	s_waitcnt lgkmcnt(8)
	v_pk_fma_f32 v[138:139], v[66:67], v[8:9], v[138:139]
	v_pk_fma_f32 v[184:185], v[68:69], v[10:11], v[184:185]
	ds_read_b128 v[8:11], v186 offset:11216
	s_waitcnt lgkmcnt(8)
	v_pk_fma_f32 v[138:139], v[70:71], v[12:13], v[138:139]
	v_pk_fma_f32 v[184:185], v[72:73], v[14:15], v[184:185]
	ds_read_b128 v[12:15], v186 offset:11232
	s_waitcnt lgkmcnt(7)
	v_pk_fma_f32 v[138:139], v[144:145], v[16:17], v[138:139]
	v_pk_fma_f32 v[184:185], v[146:147], v[18:19], v[184:185]
	ds_read_b128 v[16:19], v186 offset:11248
	s_waitcnt lgkmcnt(7)
	v_pk_fma_f32 v[138:139], v[148:149], v[20:21], v[138:139]
	v_pk_fma_f32 v[184:185], v[150:151], v[22:23], v[184:185]
	ds_read_b128 v[20:23], v186 offset:11264
	v_add_f32_e32 v187, v138, v139
	v_add_f32_e32 v30, v184, v185
	v_add_f32_e32 v152, v187, v30
	v_cndmask_b32_e64 v84, 0, 1.0, vcc
	v_cvt_pk_bf16_f32 v30, v152, v152
	ds_write_b16 v29, v30 offset:5760
	s_waitcnt lgkmcnt(8)
	v_pk_fma_f32 v[138:139], v[42:43], v[24:25], v[84:85]
	v_cmp_eq_u32_e32 vcc, 42, v88
	v_pk_mul_f32 v[184:185], v[44:45], v[26:27]
	ds_read_b128 v[24:27], v186 offset:11280
	s_waitcnt lgkmcnt(8)
	v_pk_fma_f32 v[138:139], v[46:47], v[32:33], v[138:139]
	v_pk_fma_f32 v[184:185], v[48:49], v[34:35], v[184:185]
	ds_read_b128 v[32:35], v186 offset:11296
	s_waitcnt lgkmcnt(8)
	v_pk_fma_f32 v[138:139], v[50:51], v[36:37], v[138:139]
	v_pk_fma_f32 v[184:185], v[52:53], v[38:39], v[184:185]
	ds_read_b128 v[36:39], v186 offset:11312
	s_waitcnt lgkmcnt(8)
	v_pk_fma_f32 v[138:139], v[54:55], v[80:81], v[138:139]
	v_pk_fma_f32 v[184:185], v[56:57], v[82:83], v[184:185]
	ds_read_b128 v[80:83], v186 offset:11424
	s_waitcnt lgkmcnt(8)
	v_pk_fma_f32 v[138:139], v[58:59], v[8:9], v[138:139]
	v_pk_fma_f32 v[184:185], v[60:61], v[10:11], v[184:185]
	ds_read_b128 v[8:11], v186 offset:11440
	s_waitcnt lgkmcnt(8)
	v_pk_fma_f32 v[138:139], v[62:63], v[12:13], v[138:139]
	v_pk_fma_f32 v[184:185], v[64:65], v[14:15], v[184:185]
	ds_read_b128 v[12:15], v186 offset:11456
	s_waitcnt lgkmcnt(8)
	v_pk_fma_f32 v[138:139], v[66:67], v[16:17], v[138:139]
	v_pk_fma_f32 v[184:185], v[68:69], v[18:19], v[184:185]
	ds_read_b128 v[16:19], v186 offset:11472
	s_waitcnt lgkmcnt(8)
	v_pk_fma_f32 v[138:139], v[70:71], v[20:21], v[138:139]
	v_pk_fma_f32 v[184:185], v[72:73], v[22:23], v[184:185]
	ds_read_b128 v[20:23], v186 offset:11488
	s_waitcnt lgkmcnt(7)
	v_pk_fma_f32 v[138:139], v[144:145], v[24:25], v[138:139]
	v_pk_fma_f32 v[184:185], v[146:147], v[26:27], v[184:185]
	ds_read_b128 v[24:27], v186 offset:11504
	s_waitcnt lgkmcnt(7)
	v_pk_fma_f32 v[138:139], v[148:149], v[32:33], v[138:139]
	v_pk_fma_f32 v[184:185], v[150:151], v[34:35], v[184:185]
	ds_read_b128 v[32:35], v186 offset:11520
	s_waitcnt lgkmcnt(7)
	v_fmac_f32_e32 v138, v152, v36
	ds_read_b128 v[36:39], v186 offset:11536
	v_add_f32_e32 v187, v138, v139
	v_add_f32_e32 v30, v184, v185
	v_add_f32_e32 v153, v187, v30
	v_cndmask_b32_e64 v84, 0, 1.0, vcc
	v_cvt_pk_bf16_f32 v30, v153, v153
	ds_write_b16 v29, v30 offset:5904
	s_waitcnt lgkmcnt(8)
	v_pk_fma_f32 v[138:139], v[42:43], v[80:81], v[84:85]
	v_cmp_eq_u32_e32 vcc, 43, v88
	v_pk_mul_f32 v[184:185], v[44:45], v[82:83]
	ds_read_b128 v[80:83], v186 offset:11552
	s_waitcnt lgkmcnt(8)
	v_pk_fma_f32 v[138:139], v[46:47], v[8:9], v[138:139]
	v_pk_fma_f32 v[184:185], v[48:49], v[10:11], v[184:185]
	ds_read_b128 v[8:11], v186 offset:11568
	s_waitcnt lgkmcnt(8)
	v_pk_fma_f32 v[138:139], v[50:51], v[12:13], v[138:139]
	v_pk_fma_f32 v[184:185], v[52:53], v[14:15], v[184:185]
	ds_read_b128 v[12:15], v186 offset:11584
	s_waitcnt lgkmcnt(8)
	v_pk_fma_f32 v[138:139], v[54:55], v[16:17], v[138:139]
	v_pk_fma_f32 v[184:185], v[56:57], v[18:19], v[184:185]
	ds_read_b128 v[16:19], v186 offset:11696
	s_waitcnt lgkmcnt(8)
	v_pk_fma_f32 v[138:139], v[58:59], v[20:21], v[138:139]
	v_pk_fma_f32 v[184:185], v[60:61], v[22:23], v[184:185]
	ds_read_b128 v[20:23], v186 offset:11712
	s_waitcnt lgkmcnt(8)
	v_pk_fma_f32 v[138:139], v[62:63], v[24:25], v[138:139]
	v_pk_fma_f32 v[184:185], v[64:65], v[26:27], v[184:185]
	ds_read_b128 v[24:27], v186 offset:11728
	s_waitcnt lgkmcnt(8)
	v_pk_fma_f32 v[138:139], v[66:67], v[32:33], v[138:139]
	v_pk_fma_f32 v[184:185], v[68:69], v[34:35], v[184:185]
	ds_read_b128 v[32:35], v186 offset:11744
	s_waitcnt lgkmcnt(8)
	v_pk_fma_f32 v[138:139], v[70:71], v[36:37], v[138:139]
	v_pk_fma_f32 v[184:185], v[72:73], v[38:39], v[184:185]
	ds_read_b128 v[36:39], v186 offset:11760
	s_waitcnt lgkmcnt(7)
	v_pk_fma_f32 v[138:139], v[144:145], v[80:81], v[138:139]
	v_pk_fma_f32 v[184:185], v[146:147], v[82:83], v[184:185]
	ds_read_b128 v[80:83], v186 offset:11776
	s_waitcnt lgkmcnt(7)
	v_pk_fma_f32 v[138:139], v[148:149], v[8:9], v[138:139]
	v_pk_fma_f32 v[184:185], v[150:151], v[10:11], v[184:185]
	ds_read_b128 v[8:11], v186 offset:11792
	s_waitcnt lgkmcnt(7)
	v_pk_fma_f32 v[138:139], v[152:153], v[12:13], v[138:139]
	ds_read_b128 v[12:15], v186 offset:11808
	v_add_f32_e32 v187, v138, v139
	v_add_f32_e32 v30, v184, v185
	v_add_f32_e32 v154, v187, v30
	v_cndmask_b32_e64 v84, 0, 1.0, vcc
	v_cvt_pk_bf16_f32 v30, v154, v154
	ds_write_b16 v29, v30 offset:6048
	s_waitcnt lgkmcnt(8)
; #define LAS __attribute__((address_space(3)))
; __device__ __forceinline__ bf16_t f2bf(float f) { unsigned u = __float_as_uint(f); u += 0x7FFFu + ((u >> 16) & 1u); return (bf16_t)(u >> 16); }
; __device__ __forceinline__ void phase_rwkv_ra(const Ctx& c, int p, int l) {
;     ...
;         if (w == 0) {
;             float M[64];
; #pragma unroll
;             for (int tt = 0; tt < 64; ++tt) {
;                 float a4[4] = {(lane == tt) ? 1.f : 0.f, 0.f, 0.f, 0.f};
; #pragma unroll
;                 for (int p4 = 0; p4 < (tt + 3) / 4; ++p4) {
;                     const f32x4 nv = *(const LAS f32x4*)(NfT + tt * 68 + 4 * p4);
; #pragma unroll
;                     for (int e = 0; e < 4; ++e) if (4 * p4 + e < tt) a4[e] += M[4 * p4 + e] * nv[e];
;                 }
;                 const float a = (a4[0] + a4[1]) + (a4[2] + a4[3]);
;                 M[tt] = a;
;                 MinvT[tt * RS + lane] = f2bf(a);
;             }
	v_pk_fma_f32 v[138:139], v[42:43], v[16:17], v[84:85]
	v_cmp_eq_u32_e32 vcc, 44, v88
	v_pk_mul_f32 v[184:185], v[44:45], v[18:19]
	ds_read_b128 v[16:19], v186 offset:11824
	s_waitcnt lgkmcnt(8)
	v_pk_fma_f32 v[138:139], v[46:47], v[20:21], v[138:139]
	v_pk_fma_f32 v[184:185], v[48:49], v[22:23], v[184:185]
	ds_read_b128 v[20:23], v186 offset:11840
	s_waitcnt lgkmcnt(8)
	v_pk_fma_f32 v[138:139], v[50:51], v[24:25], v[138:139]
	v_pk_fma_f32 v[184:185], v[52:53], v[26:27], v[184:185]
	ds_read_b128 v[24:27], v186 offset:11856
	s_waitcnt lgkmcnt(8)
	v_pk_fma_f32 v[138:139], v[54:55], v[32:33], v[138:139]
	v_pk_fma_f32 v[184:185], v[56:57], v[34:35], v[184:185]
	ds_read_b128 v[32:35], v186 offset:11968
	s_waitcnt lgkmcnt(8)
	v_pk_fma_f32 v[138:139], v[58:59], v[36:37], v[138:139]
	v_pk_fma_f32 v[184:185], v[60:61], v[38:39], v[184:185]
	ds_read_b128 v[36:39], v186 offset:11984
	s_waitcnt lgkmcnt(8)
	v_pk_fma_f32 v[138:139], v[62:63], v[80:81], v[138:139]
	v_pk_fma_f32 v[184:185], v[64:65], v[82:83], v[184:185]
	ds_read_b128 v[80:83], v186 offset:12000
	s_waitcnt lgkmcnt(8)
	v_pk_fma_f32 v[138:139], v[66:67], v[8:9], v[138:139]
	v_pk_fma_f32 v[184:185], v[68:69], v[10:11], v[184:185]
	ds_read_b128 v[8:11], v186 offset:12016
	s_waitcnt lgkmcnt(8)
	v_pk_fma_f32 v[138:139], v[70:71], v[12:13], v[138:139]
	v_pk_fma_f32 v[184:185], v[72:73], v[14:15], v[184:185]
	ds_read_b128 v[12:15], v186 offset:12032
	s_waitcnt lgkmcnt(7)
	v_pk_fma_f32 v[138:139], v[144:145], v[16:17], v[138:139]
	v_pk_fma_f32 v[184:185], v[146:147], v[18:19], v[184:185]
	ds_read_b128 v[16:19], v186 offset:12048
	s_waitcnt lgkmcnt(7)
	v_pk_fma_f32 v[138:139], v[148:149], v[20:21], v[138:139]
	v_pk_fma_f32 v[184:185], v[150:151], v[22:23], v[184:185]
	ds_read_b128 v[20:23], v186 offset:12064
	s_waitcnt lgkmcnt(7)
	v_pk_fma_f32 v[138:139], v[152:153], v[24:25], v[138:139]
	v_fmac_f32_e32 v184, v154, v26
	ds_read_b128 v[24:27], v186 offset:12080
	v_add_f32_e32 v187, v138, v139
	v_add_f32_e32 v30, v184, v185
	v_add_f32_e32 v155, v187, v30
	v_cndmask_b32_e64 v84, 0, 1.0, vcc
	v_cvt_pk_bf16_f32 v30, v155, v155
	ds_write_b16 v29, v30 offset:6192
	s_waitcnt lgkmcnt(8)
	v_pk_fma_f32 v[138:139], v[42:43], v[32:33], v[84:85]
	v_cmp_eq_u32_e32 vcc, 45, v88
	v_pk_mul_f32 v[184:185], v[44:45], v[34:35]
	ds_read_b128 v[32:35], v186 offset:12096
	s_waitcnt lgkmcnt(8)
	v_pk_fma_f32 v[138:139], v[46:47], v[36:37], v[138:139]
	v_pk_fma_f32 v[184:185], v[48:49], v[38:39], v[184:185]
	ds_read_b128 v[36:39], v186 offset:12112
	s_waitcnt lgkmcnt(8)
	v_pk_fma_f32 v[138:139], v[50:51], v[80:81], v[138:139]
	v_pk_fma_f32 v[184:185], v[52:53], v[82:83], v[184:185]
	ds_read_b128 v[80:83], v186 offset:12128
	s_waitcnt lgkmcnt(8)
	v_pk_fma_f32 v[138:139], v[54:55], v[8:9], v[138:139]
	v_pk_fma_f32 v[184:185], v[56:57], v[10:11], v[184:185]
	ds_read_b128 v[8:11], v186 offset:12240
	s_waitcnt lgkmcnt(8)
	v_pk_fma_f32 v[138:139], v[58:59], v[12:13], v[138:139]
	v_pk_fma_f32 v[184:185], v[60:61], v[14:15], v[184:185]
	ds_read_b128 v[12:15], v186 offset:12256
	s_waitcnt lgkmcnt(8)
	v_pk_fma_f32 v[138:139], v[62:63], v[16:17], v[138:139]
	v_pk_fma_f32 v[184:185], v[64:65], v[18:19], v[184:185]
	ds_read_b128 v[16:19], v186 offset:12272
	s_waitcnt lgkmcnt(8)
	v_pk_fma_f32 v[138:139], v[66:67], v[20:21], v[138:139]
	v_pk_fma_f32 v[184:185], v[68:69], v[22:23], v[184:185]
	ds_read_b128 v[20:23], v186 offset:12288
	s_waitcnt lgkmcnt(8)
	v_pk_fma_f32 v[138:139], v[70:71], v[24:25], v[138:139]
	v_pk_fma_f32 v[184:185], v[72:73], v[26:27], v[184:185]
	ds_read_b128 v[24:27], v186 offset:12304
	s_waitcnt lgkmcnt(7)
	v_pk_fma_f32 v[138:139], v[144:145], v[32:33], v[138:139]
	v_pk_fma_f32 v[184:185], v[146:147], v[34:35], v[184:185]
	ds_read_b128 v[32:35], v186 offset:12320
	s_waitcnt lgkmcnt(7)
	v_pk_fma_f32 v[138:139], v[148:149], v[36:37], v[138:139]
	v_pk_fma_f32 v[184:185], v[150:151], v[38:39], v[184:185]
	ds_read_b128 v[36:39], v186 offset:12336
	s_waitcnt lgkmcnt(7)
	v_pk_fma_f32 v[138:139], v[152:153], v[80:81], v[138:139]
	v_pk_fma_f32 v[184:185], v[154:155], v[82:83], v[184:185]
	ds_read_b128 v[80:83], v186 offset:12352
	v_add_f32_e32 v187, v138, v139
	v_add_f32_e32 v30, v184, v185
	v_add_f32_e32 v156, v187, v30
	v_cndmask_b32_e64 v84, 0, 1.0, vcc
	v_cvt_pk_bf16_f32 v30, v156, v156
	ds_write_b16 v29, v30 offset:6336
	s_waitcnt lgkmcnt(8)
	v_pk_fma_f32 v[138:139], v[42:43], v[8:9], v[84:85]
	v_cmp_eq_u32_e32 vcc, 46, v88
	v_pk_mul_f32 v[184:185], v[44:45], v[10:11]
	ds_read_b128 v[8:11], v186 offset:12368
	s_waitcnt lgkmcnt(8)
	v_pk_fma_f32 v[138:139], v[46:47], v[12:13], v[138:139]
	v_pk_fma_f32 v[184:185], v[48:49], v[14:15], v[184:185]
	ds_read_b128 v[12:15], v186 offset:12384
	s_waitcnt lgkmcnt(8)
	v_pk_fma_f32 v[138:139], v[50:51], v[16:17], v[138:139]
	v_pk_fma_f32 v[184:185], v[52:53], v[18:19], v[184:185]
	ds_read_b128 v[16:19], v186 offset:12400
	s_waitcnt lgkmcnt(8)
	v_pk_fma_f32 v[138:139], v[54:55], v[20:21], v[138:139]
	v_pk_fma_f32 v[184:185], v[56:57], v[22:23], v[184:185]
	ds_read_b128 v[20:23], v186 offset:12416
	s_waitcnt lgkmcnt(8)
	v_pk_fma_f32 v[138:139], v[58:59], v[24:25], v[138:139]
	v_pk_fma_f32 v[184:185], v[60:61], v[26:27], v[184:185]
	ds_read_b128 v[24:27], v186 offset:12512
	s_waitcnt lgkmcnt(8)
	v_pk_fma_f32 v[138:139], v[62:63], v[32:33], v[138:139]
	v_pk_fma_f32 v[184:185], v[64:65], v[34:35], v[184:185]
	ds_read_b128 v[32:35], v186 offset:12528
	s_waitcnt lgkmcnt(8)
	v_pk_fma_f32 v[138:139], v[66:67], v[36:37], v[138:139]
	v_pk_fma_f32 v[184:185], v[68:69], v[38:39], v[184:185]
	ds_read_b128 v[36:39], v186 offset:12544
	s_waitcnt lgkmcnt(8)
; #define LAS __attribute__((address_space(3)))
; __device__ __forceinline__ bf16_t f2bf(float f) { unsigned u = __float_as_uint(f); u += 0x7FFFu + ((u >> 16) & 1u); return (bf16_t)(u >> 16); }
; __device__ __forceinline__ void phase_rwkv_ra(const Ctx& c, int p, int l) {
;     ...
;         if (w == 0) {
;             float M[64];
; #pragma unroll
;             for (int tt = 0; tt < 64; ++tt) {
;                 float a4[4] = {(lane == tt) ? 1.f : 0.f, 0.f, 0.f, 0.f};
; #pragma unroll
;                 for (int p4 = 0; p4 < (tt + 3) / 4; ++p4) {
;                     const f32x4 nv = *(const LAS f32x4*)(NfT + tt * 68 + 4 * p4);
; #pragma unroll
;                     for (int e = 0; e < 4; ++e) if (4 * p4 + e < tt) a4[e] += M[4 * p4 + e] * nv[e];
;                 }
;                 const float a = (a4[0] + a4[1]) + (a4[2] + a4[3]);
;                 M[tt] = a;
;                 MinvT[tt * RS + lane] = f2bf(a);
;             }
	v_pk_fma_f32 v[138:139], v[70:71], v[80:81], v[138:139]
	v_pk_fma_f32 v[184:185], v[72:73], v[82:83], v[184:185]
	ds_read_b128 v[80:83], v186 offset:12560
	s_waitcnt lgkmcnt(7)
	v_pk_fma_f32 v[138:139], v[144:145], v[8:9], v[138:139]
	v_pk_fma_f32 v[184:185], v[146:147], v[10:11], v[184:185]
	ds_read_b128 v[8:11], v186 offset:12576
	s_waitcnt lgkmcnt(7)
	v_pk_fma_f32 v[138:139], v[148:149], v[12:13], v[138:139]
	v_pk_fma_f32 v[184:185], v[150:151], v[14:15], v[184:185]
	ds_read_b128 v[12:15], v186 offset:12592
	s_waitcnt lgkmcnt(7)
	v_pk_fma_f32 v[138:139], v[152:153], v[16:17], v[138:139]
	v_pk_fma_f32 v[184:185], v[154:155], v[18:19], v[184:185]
	ds_read_b128 v[16:19], v186 offset:12608
	s_waitcnt lgkmcnt(7)
	v_fmac_f32_e32 v138, v156, v20
	ds_read_b128 v[20:23], v186 offset:12624
	v_add_f32_e32 v187, v138, v139
	v_add_f32_e32 v30, v184, v185
	v_add_f32_e32 v157, v187, v30
	v_cndmask_b32_e64 v84, 0, 1.0, vcc
	v_cvt_pk_bf16_f32 v30, v157, v157
	ds_write_b16 v29, v30 offset:6480
	s_waitcnt lgkmcnt(8)
	v_pk_fma_f32 v[138:139], v[42:43], v[24:25], v[84:85]
	v_cmp_eq_u32_e32 vcc, 47, v88
	v_pk_mul_f32 v[184:185], v[44:45], v[26:27]
	ds_read_b128 v[24:27], v186 offset:12640
	s_waitcnt lgkmcnt(8)
	v_pk_fma_f32 v[138:139], v[46:47], v[32:33], v[138:139]
	v_pk_fma_f32 v[184:185], v[48:49], v[34:35], v[184:185]
	ds_read_b128 v[32:35], v186 offset:12656
	s_waitcnt lgkmcnt(8)
	v_pk_fma_f32 v[138:139], v[50:51], v[36:37], v[138:139]
	v_pk_fma_f32 v[184:185], v[52:53], v[38:39], v[184:185]
	ds_read_b128 v[36:39], v186 offset:12672
	s_waitcnt lgkmcnt(8)
	v_pk_fma_f32 v[138:139], v[54:55], v[80:81], v[138:139]
	v_pk_fma_f32 v[184:185], v[56:57], v[82:83], v[184:185]
	ds_read_b128 v[80:83], v186 offset:12688
	s_waitcnt lgkmcnt(8)
	v_pk_fma_f32 v[138:139], v[58:59], v[8:9], v[138:139]
	v_pk_fma_f32 v[184:185], v[60:61], v[10:11], v[184:185]
	ds_read_b128 v[8:11], v186 offset:12784
	s_waitcnt lgkmcnt(8)
	v_pk_fma_f32 v[138:139], v[62:63], v[12:13], v[138:139]
	v_pk_fma_f32 v[184:185], v[64:65], v[14:15], v[184:185]
	ds_read_b128 v[12:15], v186 offset:12800
	s_waitcnt lgkmcnt(8)
	v_pk_fma_f32 v[138:139], v[66:67], v[16:17], v[138:139]
	v_pk_fma_f32 v[184:185], v[68:69], v[18:19], v[184:185]
	ds_read_b128 v[16:19], v186 offset:12816
	s_waitcnt lgkmcnt(8)
	v_pk_fma_f32 v[138:139], v[70:71], v[20:21], v[138:139]
	v_pk_fma_f32 v[184:185], v[72:73], v[22:23], v[184:185]
	ds_read_b128 v[20:23], v186 offset:12832
	s_waitcnt lgkmcnt(7)
	v_pk_fma_f32 v[138:139], v[144:145], v[24:25], v[138:139]
	v_pk_fma_f32 v[184:185], v[146:147], v[26:27], v[184:185]
	ds_read_b128 v[24:27], v186 offset:12848
	s_waitcnt lgkmcnt(7)
	v_pk_fma_f32 v[138:139], v[148:149], v[32:33], v[138:139]
	v_pk_fma_f32 v[184:185], v[150:151], v[34:35], v[184:185]
	ds_read_b128 v[32:35], v186 offset:12864
	s_waitcnt lgkmcnt(7)
	v_pk_fma_f32 v[138:139], v[152:153], v[36:37], v[138:139]
	v_pk_fma_f32 v[184:185], v[154:155], v[38:39], v[184:185]
	ds_read_b128 v[36:39], v186 offset:12880
	s_waitcnt lgkmcnt(7)
	v_pk_fma_f32 v[138:139], v[156:157], v[80:81], v[138:139]
	ds_read_b128 v[80:83], v186 offset:12896
	v_add_f32_e32 v187, v138, v139
	v_add_f32_e32 v30, v184, v185
	v_add_f32_e32 v158, v187, v30
	v_cndmask_b32_e64 v84, 0, 1.0, vcc
	v_cvt_pk_bf16_f32 v30, v158, v158
	ds_write_b16 v29, v30 offset:6624
	s_waitcnt lgkmcnt(8)
	v_pk_fma_f32 v[138:139], v[42:43], v[8:9], v[84:85]
	v_cmp_eq_u32_e32 vcc, 48, v88
	v_pk_mul_f32 v[184:185], v[44:45], v[10:11]
	ds_read_b128 v[8:11], v186 offset:12912
	s_waitcnt lgkmcnt(8)
	v_pk_fma_f32 v[138:139], v[46:47], v[12:13], v[138:139]
	v_pk_fma_f32 v[184:185], v[48:49], v[14:15], v[184:185]
	ds_read_b128 v[12:15], v186 offset:12928
	s_waitcnt lgkmcnt(8)
	v_pk_fma_f32 v[138:139], v[50:51], v[16:17], v[138:139]
	v_pk_fma_f32 v[184:185], v[52:53], v[18:19], v[184:185]
	ds_read_b128 v[16:19], v186 offset:12944
	s_waitcnt lgkmcnt(8)
	v_pk_fma_f32 v[138:139], v[54:55], v[20:21], v[138:139]
	v_pk_fma_f32 v[184:185], v[56:57], v[22:23], v[184:185]
	ds_read_b128 v[20:23], v186 offset:12960
	s_waitcnt lgkmcnt(8)
	v_pk_fma_f32 v[138:139], v[58:59], v[24:25], v[138:139]
	v_pk_fma_f32 v[184:185], v[60:61], v[26:27], v[184:185]
	ds_read_b128 v[24:27], v186 offset:13056
	s_waitcnt lgkmcnt(8)
	v_pk_fma_f32 v[138:139], v[62:63], v[32:33], v[138:139]
	v_pk_fma_f32 v[184:185], v[64:65], v[34:35], v[184:185]
	ds_read_b128 v[32:35], v186 offset:13072
	s_waitcnt lgkmcnt(8)
	v_pk_fma_f32 v[138:139], v[66:67], v[36:37], v[138:139]
	v_pk_fma_f32 v[184:185], v[68:69], v[38:39], v[184:185]
	ds_read_b128 v[36:39], v186 offset:13088
	s_waitcnt lgkmcnt(8)
	v_pk_fma_f32 v[138:139], v[70:71], v[80:81], v[138:139]
	v_pk_fma_f32 v[184:185], v[72:73], v[82:83], v[184:185]
	ds_read_b128 v[80:83], v186 offset:13104
	s_waitcnt lgkmcnt(7)
	v_pk_fma_f32 v[138:139], v[144:145], v[8:9], v[138:139]
	v_pk_fma_f32 v[184:185], v[146:147], v[10:11], v[184:185]
	ds_read_b128 v[8:11], v186 offset:13120
	s_waitcnt lgkmcnt(7)
	v_pk_fma_f32 v[138:139], v[148:149], v[12:13], v[138:139]
	v_pk_fma_f32 v[184:185], v[150:151], v[14:15], v[184:185]
	ds_read_b128 v[12:15], v186 offset:13136
	s_waitcnt lgkmcnt(7)
	v_pk_fma_f32 v[138:139], v[152:153], v[16:17], v[138:139]
	v_pk_fma_f32 v[184:185], v[154:155], v[18:19], v[184:185]
	ds_read_b128 v[16:19], v186 offset:13152
	s_waitcnt lgkmcnt(7)
	v_pk_fma_f32 v[138:139], v[156:157], v[20:21], v[138:139]
	v_fmac_f32_e32 v184, v158, v22
	ds_read_b128 v[20:23], v186 offset:13168
	v_add_f32_e32 v187, v138, v139
	v_add_f32_e32 v30, v184, v185
	v_add_f32_e32 v159, v187, v30
	v_cndmask_b32_e64 v84, 0, 1.0, vcc
	v_cvt_pk_bf16_f32 v30, v159, v159
	ds_write_b16 v29, v30 offset:6768
	s_waitcnt lgkmcnt(8)
; #define LAS __attribute__((address_space(3)))
; __device__ __forceinline__ bf16_t f2bf(float f) { unsigned u = __float_as_uint(f); u += 0x7FFFu + ((u >> 16) & 1u); return (bf16_t)(u >> 16); }
; __device__ __forceinline__ void phase_rwkv_ra(const Ctx& c, int p, int l) {
;     ...
;         if (w == 0) {
;             float M[64];
; #pragma unroll
;             for (int tt = 0; tt < 64; ++tt) {
;                 float a4[4] = {(lane == tt) ? 1.f : 0.f, 0.f, 0.f, 0.f};
; #pragma unroll
;                 for (int p4 = 0; p4 < (tt + 3) / 4; ++p4) {
;                     const f32x4 nv = *(const LAS f32x4*)(NfT + tt * 68 + 4 * p4);
; #pragma unroll
;                     for (int e = 0; e < 4; ++e) if (4 * p4 + e < tt) a4[e] += M[4 * p4 + e] * nv[e];
;                 }
;                 const float a = (a4[0] + a4[1]) + (a4[2] + a4[3]);
;                 M[tt] = a;
;                 MinvT[tt * RS + lane] = f2bf(a);
;             }
	v_pk_fma_f32 v[138:139], v[42:43], v[24:25], v[84:85]
	v_cmp_eq_u32_e32 vcc, 49, v88
	v_pk_mul_f32 v[184:185], v[44:45], v[26:27]
	ds_read_b128 v[24:27], v186 offset:13184
	s_waitcnt lgkmcnt(8)
	v_pk_fma_f32 v[138:139], v[46:47], v[32:33], v[138:139]
	v_pk_fma_f32 v[184:185], v[48:49], v[34:35], v[184:185]
	ds_read_b128 v[32:35], v186 offset:13200
	s_waitcnt lgkmcnt(8)
	v_pk_fma_f32 v[138:139], v[50:51], v[36:37], v[138:139]
	v_pk_fma_f32 v[184:185], v[52:53], v[38:39], v[184:185]
	ds_read_b128 v[36:39], v186 offset:13216
	s_waitcnt lgkmcnt(8)
	v_pk_fma_f32 v[138:139], v[54:55], v[80:81], v[138:139]
	v_pk_fma_f32 v[184:185], v[56:57], v[82:83], v[184:185]
	ds_read_b128 v[80:83], v186 offset:13232
	s_waitcnt lgkmcnt(8)
	v_pk_fma_f32 v[138:139], v[58:59], v[8:9], v[138:139]
	v_pk_fma_f32 v[184:185], v[60:61], v[10:11], v[184:185]
	ds_read_b128 v[8:11], v186 offset:13328
	s_waitcnt lgkmcnt(8)
	v_pk_fma_f32 v[138:139], v[62:63], v[12:13], v[138:139]
	v_pk_fma_f32 v[184:185], v[64:65], v[14:15], v[184:185]
	ds_read_b128 v[12:15], v186 offset:13344
	s_waitcnt lgkmcnt(8)
	v_pk_fma_f32 v[138:139], v[66:67], v[16:17], v[138:139]
	v_pk_fma_f32 v[184:185], v[68:69], v[18:19], v[184:185]
	ds_read_b128 v[16:19], v186 offset:13360
	s_waitcnt lgkmcnt(8)
	v_pk_fma_f32 v[138:139], v[70:71], v[20:21], v[138:139]
	v_pk_fma_f32 v[184:185], v[72:73], v[22:23], v[184:185]
	ds_read_b128 v[20:23], v186 offset:13376
	s_waitcnt lgkmcnt(7)
	v_pk_fma_f32 v[138:139], v[144:145], v[24:25], v[138:139]
	v_pk_fma_f32 v[184:185], v[146:147], v[26:27], v[184:185]
	ds_read_b128 v[24:27], v186 offset:13392
	s_waitcnt lgkmcnt(7)
	v_pk_fma_f32 v[138:139], v[148:149], v[32:33], v[138:139]
	v_pk_fma_f32 v[184:185], v[150:151], v[34:35], v[184:185]
	ds_read_b128 v[32:35], v186 offset:13408
	s_waitcnt lgkmcnt(7)
	v_pk_fma_f32 v[138:139], v[152:153], v[36:37], v[138:139]
	v_pk_fma_f32 v[184:185], v[154:155], v[38:39], v[184:185]
	ds_read_b128 v[36:39], v186 offset:13424
	s_waitcnt lgkmcnt(7)
	v_pk_fma_f32 v[138:139], v[156:157], v[80:81], v[138:139]
	v_pk_fma_f32 v[184:185], v[158:159], v[82:83], v[184:185]
	ds_read_b128 v[80:83], v186 offset:13440
	v_add_f32_e32 v187, v138, v139
	v_add_f32_e32 v30, v184, v185
	v_add_f32_e32 v160, v187, v30
	v_cndmask_b32_e64 v84, 0, 1.0, vcc
	v_cvt_pk_bf16_f32 v30, v160, v160
	ds_write_b16 v29, v30 offset:6912
	s_waitcnt lgkmcnt(8)
	v_pk_fma_f32 v[138:139], v[42:43], v[8:9], v[84:85]
	v_cmp_eq_u32_e32 vcc, 50, v88
	v_pk_mul_f32 v[184:185], v[44:45], v[10:11]
	ds_read_b128 v[8:11], v186 offset:13456
	s_waitcnt lgkmcnt(8)
	v_pk_fma_f32 v[138:139], v[46:47], v[12:13], v[138:139]
	v_pk_fma_f32 v[184:185], v[48:49], v[14:15], v[184:185]
	ds_read_b128 v[12:15], v186 offset:13472
	s_waitcnt lgkmcnt(8)
	v_pk_fma_f32 v[138:139], v[50:51], v[16:17], v[138:139]
	v_pk_fma_f32 v[184:185], v[52:53], v[18:19], v[184:185]
	ds_read_b128 v[16:19], v186 offset:13488
	s_waitcnt lgkmcnt(8)
	v_pk_fma_f32 v[138:139], v[54:55], v[20:21], v[138:139]
	v_pk_fma_f32 v[184:185], v[56:57], v[22:23], v[184:185]
	ds_read_b128 v[20:23], v186 offset:13504
	s_waitcnt lgkmcnt(8)
	v_pk_fma_f32 v[138:139], v[58:59], v[24:25], v[138:139]
	v_pk_fma_f32 v[184:185], v[60:61], v[26:27], v[184:185]
	ds_read_b128 v[24:27], v186 offset:13520
	s_waitcnt lgkmcnt(8)
	v_pk_fma_f32 v[138:139], v[62:63], v[32:33], v[138:139]
	v_pk_fma_f32 v[184:185], v[64:65], v[34:35], v[184:185]
	ds_read_b128 v[32:35], v186 offset:13600
	s_waitcnt lgkmcnt(8)
	v_pk_fma_f32 v[138:139], v[66:67], v[36:37], v[138:139]
	v_pk_fma_f32 v[184:185], v[68:69], v[38:39], v[184:185]
	ds_read_b128 v[36:39], v186 offset:13616
	s_waitcnt lgkmcnt(8)
	v_pk_fma_f32 v[138:139], v[70:71], v[80:81], v[138:139]
	v_pk_fma_f32 v[184:185], v[72:73], v[82:83], v[184:185]
	ds_read_b128 v[80:83], v186 offset:13632
	s_waitcnt lgkmcnt(7)
	v_pk_fma_f32 v[138:139], v[144:145], v[8:9], v[138:139]
	v_pk_fma_f32 v[184:185], v[146:147], v[10:11], v[184:185]
	ds_read_b128 v[8:11], v186 offset:13648
	s_waitcnt lgkmcnt(7)
	v_pk_fma_f32 v[138:139], v[148:149], v[12:13], v[138:139]
	v_pk_fma_f32 v[184:185], v[150:151], v[14:15], v[184:185]
	ds_read_b128 v[12:15], v186 offset:13664
	s_waitcnt lgkmcnt(7)
	v_pk_fma_f32 v[138:139], v[152:153], v[16:17], v[138:139]
	v_pk_fma_f32 v[184:185], v[154:155], v[18:19], v[184:185]
	ds_read_b128 v[16:19], v186 offset:13680
	s_waitcnt lgkmcnt(7)
	v_pk_fma_f32 v[138:139], v[156:157], v[20:21], v[138:139]
	v_pk_fma_f32 v[184:185], v[158:159], v[22:23], v[184:185]
	ds_read_b128 v[20:23], v186 offset:13696
	s_waitcnt lgkmcnt(7)
	v_fmac_f32_e32 v138, v160, v24
	ds_read_b128 v[24:27], v186 offset:13712
	v_add_f32_e32 v187, v138, v139
	v_add_f32_e32 v30, v184, v185
	v_add_f32_e32 v161, v187, v30
	v_cndmask_b32_e64 v84, 0, 1.0, vcc
	v_cvt_pk_bf16_f32 v30, v161, v161
	ds_write_b16 v29, v30 offset:7056
	s_waitcnt lgkmcnt(8)
	v_pk_fma_f32 v[138:139], v[42:43], v[32:33], v[84:85]
	v_cmp_eq_u32_e32 vcc, 51, v88
	v_pk_mul_f32 v[184:185], v[44:45], v[34:35]
	ds_read_b128 v[32:35], v186 offset:13728
	s_waitcnt lgkmcnt(8)
	v_pk_fma_f32 v[138:139], v[46:47], v[36:37], v[138:139]
	v_pk_fma_f32 v[184:185], v[48:49], v[38:39], v[184:185]
	ds_read_b128 v[36:39], v186 offset:13744
	s_waitcnt lgkmcnt(8)
	v_pk_fma_f32 v[138:139], v[50:51], v[80:81], v[138:139]
	v_pk_fma_f32 v[184:185], v[52:53], v[82:83], v[184:185]
	ds_read_b128 v[80:83], v186 offset:13760
	s_waitcnt lgkmcnt(8)
	v_pk_fma_f32 v[138:139], v[54:55], v[8:9], v[138:139]
	v_pk_fma_f32 v[184:185], v[56:57], v[10:11], v[184:185]
	ds_read_b128 v[8:11], v186 offset:13776
	s_waitcnt lgkmcnt(8)
; #define LAS __attribute__((address_space(3)))
; __device__ __forceinline__ bf16_t f2bf(float f) { unsigned u = __float_as_uint(f); u += 0x7FFFu + ((u >> 16) & 1u); return (bf16_t)(u >> 16); }
; __device__ __forceinline__ void phase_rwkv_ra(const Ctx& c, int p, int l) {
;     ...
;         if (w == 0) {
;             float M[64];
; #pragma unroll
;             for (int tt = 0; tt < 64; ++tt) {
;                 float a4[4] = {(lane == tt) ? 1.f : 0.f, 0.f, 0.f, 0.f};
; #pragma unroll
;                 for (int p4 = 0; p4 < (tt + 3) / 4; ++p4) {
;                     const f32x4 nv = *(const LAS f32x4*)(NfT + tt * 68 + 4 * p4);
; #pragma unroll
;                     for (int e = 0; e < 4; ++e) if (4 * p4 + e < tt) a4[e] += M[4 * p4 + e] * nv[e];
;                 }
;                 const float a = (a4[0] + a4[1]) + (a4[2] + a4[3]);
;                 M[tt] = a;
;                 MinvT[tt * RS + lane] = f2bf(a);
;             }
	v_pk_fma_f32 v[138:139], v[58:59], v[12:13], v[138:139]
	v_pk_fma_f32 v[184:185], v[60:61], v[14:15], v[184:185]
	ds_read_b128 v[12:15], v186 offset:13792
	s_waitcnt lgkmcnt(8)
	v_pk_fma_f32 v[138:139], v[62:63], v[16:17], v[138:139]
	v_pk_fma_f32 v[184:185], v[64:65], v[18:19], v[184:185]
	ds_read_b128 v[16:19], v186 offset:13872
	s_waitcnt lgkmcnt(8)
	v_pk_fma_f32 v[138:139], v[66:67], v[20:21], v[138:139]
	v_pk_fma_f32 v[184:185], v[68:69], v[22:23], v[184:185]
	ds_read_b128 v[20:23], v186 offset:13888
	s_waitcnt lgkmcnt(8)
	v_pk_fma_f32 v[138:139], v[70:71], v[24:25], v[138:139]
	v_pk_fma_f32 v[184:185], v[72:73], v[26:27], v[184:185]
	ds_read_b128 v[24:27], v186 offset:13904
	s_waitcnt lgkmcnt(7)
	v_pk_fma_f32 v[138:139], v[144:145], v[32:33], v[138:139]
	v_pk_fma_f32 v[184:185], v[146:147], v[34:35], v[184:185]
	ds_read_b128 v[32:35], v186 offset:13920
	s_waitcnt lgkmcnt(7)
	v_pk_fma_f32 v[138:139], v[148:149], v[36:37], v[138:139]
	v_pk_fma_f32 v[184:185], v[150:151], v[38:39], v[184:185]
	ds_read_b128 v[36:39], v186 offset:13936
	s_waitcnt lgkmcnt(7)
	v_pk_fma_f32 v[138:139], v[152:153], v[80:81], v[138:139]
	v_pk_fma_f32 v[184:185], v[154:155], v[82:83], v[184:185]
	ds_read_b128 v[80:83], v186 offset:13952
	s_waitcnt lgkmcnt(7)
	v_pk_fma_f32 v[138:139], v[156:157], v[8:9], v[138:139]
	v_pk_fma_f32 v[184:185], v[158:159], v[10:11], v[184:185]
	ds_read_b128 v[8:11], v186 offset:13968
	s_waitcnt lgkmcnt(7)
	v_pk_fma_f32 v[138:139], v[160:161], v[12:13], v[138:139]
	ds_read_b128 v[12:15], v186 offset:13984
	v_add_f32_e32 v187, v138, v139
	v_add_f32_e32 v30, v184, v185
	v_add_f32_e32 v124, v187, v30
	v_cndmask_b32_e64 v84, 0, 1.0, vcc
	v_cvt_pk_bf16_f32 v30, v124, v124
	ds_write_b16 v29, v30 offset:7200
	s_waitcnt lgkmcnt(8)
	v_pk_fma_f32 v[138:139], v[42:43], v[16:17], v[84:85]
	v_cmp_eq_u32_e32 vcc, 52, v88
	v_pk_mul_f32 v[184:185], v[44:45], v[18:19]
	ds_read_b128 v[16:19], v186 offset:14000
	s_waitcnt lgkmcnt(8)
	v_pk_fma_f32 v[138:139], v[46:47], v[20:21], v[138:139]
	v_pk_fma_f32 v[184:185], v[48:49], v[22:23], v[184:185]
	ds_read_b128 v[20:23], v186 offset:14016
	s_waitcnt lgkmcnt(8)
	v_pk_fma_f32 v[138:139], v[50:51], v[24:25], v[138:139]
	v_pk_fma_f32 v[184:185], v[52:53], v[26:27], v[184:185]
	ds_read_b128 v[24:27], v186 offset:14032
	s_waitcnt lgkmcnt(8)
	v_pk_fma_f32 v[138:139], v[54:55], v[32:33], v[138:139]
	v_pk_fma_f32 v[184:185], v[56:57], v[34:35], v[184:185]
	ds_read_b128 v[32:35], v186 offset:14048
	s_waitcnt lgkmcnt(8)
	v_pk_fma_f32 v[138:139], v[58:59], v[36:37], v[138:139]
	v_pk_fma_f32 v[184:185], v[60:61], v[38:39], v[184:185]
	ds_read_b128 v[36:39], v186 offset:14064
	s_waitcnt lgkmcnt(8)
	v_pk_fma_f32 v[138:139], v[62:63], v[80:81], v[138:139]
	v_pk_fma_f32 v[184:185], v[64:65], v[82:83], v[184:185]
	ds_read_b128 v[80:83], v186 offset:14144
	s_waitcnt lgkmcnt(8)
	v_pk_fma_f32 v[138:139], v[66:67], v[8:9], v[138:139]
	v_pk_fma_f32 v[184:185], v[68:69], v[10:11], v[184:185]
	ds_read_b128 v[8:11], v186 offset:14160
	s_waitcnt lgkmcnt(8)
	v_pk_fma_f32 v[138:139], v[70:71], v[12:13], v[138:139]
	v_pk_fma_f32 v[184:185], v[72:73], v[14:15], v[184:185]
	ds_read_b128 v[12:15], v186 offset:14176
	s_waitcnt lgkmcnt(7)
	v_pk_fma_f32 v[138:139], v[144:145], v[16:17], v[138:139]
	v_pk_fma_f32 v[184:185], v[146:147], v[18:19], v[184:185]
	ds_read_b128 v[16:19], v186 offset:14192
	s_waitcnt lgkmcnt(7)
	v_pk_fma_f32 v[138:139], v[148:149], v[20:21], v[138:139]
	v_pk_fma_f32 v[184:185], v[150:151], v[22:23], v[184:185]
	ds_read_b128 v[20:23], v186 offset:14208
	s_waitcnt lgkmcnt(7)
	v_pk_fma_f32 v[138:139], v[152:153], v[24:25], v[138:139]
	v_pk_fma_f32 v[184:185], v[154:155], v[26:27], v[184:185]
	ds_read_b128 v[24:27], v186 offset:14224
	s_waitcnt lgkmcnt(7)
	v_pk_fma_f32 v[138:139], v[156:157], v[32:33], v[138:139]
	v_pk_fma_f32 v[184:185], v[158:159], v[34:35], v[184:185]
	ds_read_b128 v[32:35], v186 offset:14240
	s_waitcnt lgkmcnt(7)
	v_pk_fma_f32 v[138:139], v[160:161], v[36:37], v[138:139]
	v_fmac_f32_e32 v184, v124, v38
	ds_read_b128 v[36:39], v186 offset:14256
	v_add_f32_e32 v187, v138, v139
	v_add_f32_e32 v30, v184, v185
	v_add_f32_e32 v125, v187, v30
	v_cndmask_b32_e64 v84, 0, 1.0, vcc
	v_cvt_pk_bf16_f32 v30, v125, v125
	ds_write_b16 v29, v30 offset:7344
	s_waitcnt lgkmcnt(8)
	v_pk_fma_f32 v[138:139], v[42:43], v[80:81], v[84:85]
	v_cmp_eq_u32_e32 vcc, 53, v88
	v_pk_mul_f32 v[184:185], v[44:45], v[82:83]
	ds_read_b128 v[80:83], v186 offset:14272
	s_waitcnt lgkmcnt(8)
	v_pk_fma_f32 v[138:139], v[46:47], v[8:9], v[138:139]
	v_pk_fma_f32 v[184:185], v[48:49], v[10:11], v[184:185]
	ds_read_b128 v[8:11], v186 offset:14288
	s_waitcnt lgkmcnt(8)
	v_pk_fma_f32 v[138:139], v[50:51], v[12:13], v[138:139]
	v_pk_fma_f32 v[184:185], v[52:53], v[14:15], v[184:185]
	ds_read_b128 v[12:15], v186 offset:14304
	s_waitcnt lgkmcnt(8)
	v_pk_fma_f32 v[138:139], v[54:55], v[16:17], v[138:139]
	v_pk_fma_f32 v[184:185], v[56:57], v[18:19], v[184:185]
	ds_read_b128 v[16:19], v186 offset:14320
	s_waitcnt lgkmcnt(8)
	v_pk_fma_f32 v[138:139], v[58:59], v[20:21], v[138:139]
	v_pk_fma_f32 v[184:185], v[60:61], v[22:23], v[184:185]
	ds_read_b128 v[20:23], v186 offset:14336
	s_waitcnt lgkmcnt(8)
	v_pk_fma_f32 v[138:139], v[62:63], v[24:25], v[138:139]
	v_pk_fma_f32 v[184:185], v[64:65], v[26:27], v[184:185]
	ds_read_b128 v[24:27], v186 offset:14416
	s_waitcnt lgkmcnt(8)
	v_pk_fma_f32 v[138:139], v[66:67], v[32:33], v[138:139]
	v_pk_fma_f32 v[184:185], v[68:69], v[34:35], v[184:185]
	ds_read_b128 v[32:35], v186 offset:14432
	s_waitcnt lgkmcnt(8)
	v_pk_fma_f32 v[138:139], v[70:71], v[36:37], v[138:139]
	v_pk_fma_f32 v[184:185], v[72:73], v[38:39], v[184:185]
	ds_read_b128 v[36:39], v186 offset:14448
	s_waitcnt lgkmcnt(7)
; #define LAS __attribute__((address_space(3)))
; __device__ __forceinline__ bf16_t f2bf(float f) { unsigned u = __float_as_uint(f); u += 0x7FFFu + ((u >> 16) & 1u); return (bf16_t)(u >> 16); }
; __device__ __forceinline__ void phase_rwkv_ra(const Ctx& c, int p, int l) {
;     ...
;         if (w == 0) {
;             float M[64];
; #pragma unroll
;             for (int tt = 0; tt < 64; ++tt) {
;                 float a4[4] = {(lane == tt) ? 1.f : 0.f, 0.f, 0.f, 0.f};
; #pragma unroll
;                 for (int p4 = 0; p4 < (tt + 3) / 4; ++p4) {
;                     const f32x4 nv = *(const LAS f32x4*)(NfT + tt * 68 + 4 * p4);
; #pragma unroll
;                     for (int e = 0; e < 4; ++e) if (4 * p4 + e < tt) a4[e] += M[4 * p4 + e] * nv[e];
;                 }
;                 const float a = (a4[0] + a4[1]) + (a4[2] + a4[3]);
;                 M[tt] = a;
;                 MinvT[tt * RS + lane] = f2bf(a);
;             }
	v_pk_fma_f32 v[138:139], v[144:145], v[80:81], v[138:139]
	v_pk_fma_f32 v[184:185], v[146:147], v[82:83], v[184:185]
	ds_read_b128 v[80:83], v186 offset:14464
	s_waitcnt lgkmcnt(7)
	v_pk_fma_f32 v[138:139], v[148:149], v[8:9], v[138:139]
	v_pk_fma_f32 v[184:185], v[150:151], v[10:11], v[184:185]
	ds_read_b128 v[8:11], v186 offset:14480
	s_waitcnt lgkmcnt(7)
	v_pk_fma_f32 v[138:139], v[152:153], v[12:13], v[138:139]
	v_pk_fma_f32 v[184:185], v[154:155], v[14:15], v[184:185]
	ds_read_b128 v[12:15], v186 offset:14496
	s_waitcnt lgkmcnt(7)
	v_pk_fma_f32 v[138:139], v[156:157], v[16:17], v[138:139]
	v_pk_fma_f32 v[184:185], v[158:159], v[18:19], v[184:185]
	ds_read_b128 v[16:19], v186 offset:14512
	s_waitcnt lgkmcnt(7)
	v_pk_fma_f32 v[138:139], v[160:161], v[20:21], v[138:139]
	v_pk_fma_f32 v[184:185], v[124:125], v[22:23], v[184:185]
	ds_read_b128 v[20:23], v186 offset:14528
	v_add_f32_e32 v187, v138, v139
	v_add_f32_e32 v30, v184, v185
	v_add_f32_e32 v126, v187, v30
	v_cndmask_b32_e64 v84, 0, 1.0, vcc
	v_cvt_pk_bf16_f32 v30, v126, v126
	ds_write_b16 v29, v30 offset:7488
	s_waitcnt lgkmcnt(8)
	v_pk_fma_f32 v[138:139], v[42:43], v[24:25], v[84:85]
	v_cmp_eq_u32_e32 vcc, 54, v88
	v_pk_mul_f32 v[184:185], v[44:45], v[26:27]
	ds_read_b128 v[24:27], v186 offset:14544
	s_waitcnt lgkmcnt(8)
	v_pk_fma_f32 v[138:139], v[46:47], v[32:33], v[138:139]
	v_pk_fma_f32 v[184:185], v[48:49], v[34:35], v[184:185]
	ds_read_b128 v[32:35], v186 offset:14560
	s_waitcnt lgkmcnt(8)
	v_pk_fma_f32 v[138:139], v[50:51], v[36:37], v[138:139]
	v_pk_fma_f32 v[184:185], v[52:53], v[38:39], v[184:185]
	ds_read_b128 v[36:39], v186 offset:14576
	s_waitcnt lgkmcnt(8)
	v_pk_fma_f32 v[138:139], v[54:55], v[80:81], v[138:139]
	v_pk_fma_f32 v[184:185], v[56:57], v[82:83], v[184:185]
	ds_read_b128 v[80:83], v186 offset:14592
	s_waitcnt lgkmcnt(8)
	v_pk_fma_f32 v[138:139], v[58:59], v[8:9], v[138:139]
	v_pk_fma_f32 v[184:185], v[60:61], v[10:11], v[184:185]
	ds_read_b128 v[8:11], v186 offset:14608
	s_waitcnt lgkmcnt(8)
	v_pk_fma_f32 v[138:139], v[62:63], v[12:13], v[138:139]
	v_pk_fma_f32 v[184:185], v[64:65], v[14:15], v[184:185]
	ds_read_b128 v[12:15], v186 offset:14624
	s_waitcnt lgkmcnt(8)
	v_pk_fma_f32 v[138:139], v[66:67], v[16:17], v[138:139]
	v_pk_fma_f32 v[184:185], v[68:69], v[18:19], v[184:185]
	ds_read_b128 v[16:19], v186 offset:14688
	s_waitcnt lgkmcnt(8)
	v_pk_fma_f32 v[138:139], v[70:71], v[20:21], v[138:139]
	v_pk_fma_f32 v[184:185], v[72:73], v[22:23], v[184:185]
	ds_read_b128 v[20:23], v186 offset:14704
	s_waitcnt lgkmcnt(7)
	v_pk_fma_f32 v[138:139], v[144:145], v[24:25], v[138:139]
	v_pk_fma_f32 v[184:185], v[146:147], v[26:27], v[184:185]
	ds_read_b128 v[24:27], v186 offset:14720
	s_waitcnt lgkmcnt(7)
	v_pk_fma_f32 v[138:139], v[148:149], v[32:33], v[138:139]
	v_pk_fma_f32 v[184:185], v[150:151], v[34:35], v[184:185]
	ds_read_b128 v[32:35], v186 offset:14736
	s_waitcnt lgkmcnt(7)
	v_pk_fma_f32 v[138:139], v[152:153], v[36:37], v[138:139]
	v_pk_fma_f32 v[184:185], v[154:155], v[38:39], v[184:185]
	ds_read_b128 v[36:39], v186 offset:14752
	s_waitcnt lgkmcnt(7)
	v_pk_fma_f32 v[138:139], v[156:157], v[80:81], v[138:139]
	v_pk_fma_f32 v[184:185], v[158:159], v[82:83], v[184:185]
	ds_read_b128 v[80:83], v186 offset:14768
	s_waitcnt lgkmcnt(7)
	v_pk_fma_f32 v[138:139], v[160:161], v[8:9], v[138:139]
	v_pk_fma_f32 v[184:185], v[124:125], v[10:11], v[184:185]
	ds_read_b128 v[8:11], v186 offset:14784
	s_waitcnt lgkmcnt(7)
	v_fmac_f32_e32 v138, v126, v12
	ds_read_b128 v[12:15], v186 offset:14800
	v_add_f32_e32 v187, v138, v139
	v_add_f32_e32 v30, v184, v185
	v_add_f32_e32 v127, v187, v30
	v_cndmask_b32_e64 v84, 0, 1.0, vcc
	v_cvt_pk_bf16_f32 v30, v127, v127
	ds_write_b16 v29, v30 offset:7632
	s_waitcnt lgkmcnt(8)
	v_pk_fma_f32 v[138:139], v[42:43], v[16:17], v[84:85]
	v_cmp_eq_u32_e32 vcc, 55, v88
	v_pk_mul_f32 v[184:185], v[44:45], v[18:19]
	ds_read_b128 v[16:19], v186 offset:14816
	s_waitcnt lgkmcnt(8)
	v_pk_fma_f32 v[138:139], v[46:47], v[20:21], v[138:139]
	v_pk_fma_f32 v[184:185], v[48:49], v[22:23], v[184:185]
	ds_read_b128 v[20:23], v186 offset:14832
	s_waitcnt lgkmcnt(8)
	v_pk_fma_f32 v[138:139], v[50:51], v[24:25], v[138:139]
	v_pk_fma_f32 v[184:185], v[52:53], v[26:27], v[184:185]
	ds_read_b128 v[24:27], v186 offset:14848
	s_waitcnt lgkmcnt(8)
	v_pk_fma_f32 v[138:139], v[54:55], v[32:33], v[138:139]
	v_pk_fma_f32 v[184:185], v[56:57], v[34:35], v[184:185]
	ds_read_b128 v[32:35], v186 offset:14864
	s_waitcnt lgkmcnt(8)
	v_pk_fma_f32 v[138:139], v[58:59], v[36:37], v[138:139]
	v_pk_fma_f32 v[184:185], v[60:61], v[38:39], v[184:185]
	ds_read_b128 v[36:39], v186 offset:14880
	s_waitcnt lgkmcnt(8)
	v_pk_fma_f32 v[138:139], v[62:63], v[80:81], v[138:139]
	v_pk_fma_f32 v[184:185], v[64:65], v[82:83], v[184:185]
	ds_read_b128 v[80:83], v186 offset:14896
	s_waitcnt lgkmcnt(8)
	v_pk_fma_f32 v[138:139], v[66:67], v[8:9], v[138:139]
	v_pk_fma_f32 v[184:185], v[68:69], v[10:11], v[184:185]
	ds_read_b128 v[8:11], v186 offset:14960
	s_waitcnt lgkmcnt(8)
	v_pk_fma_f32 v[138:139], v[70:71], v[12:13], v[138:139]
	v_pk_fma_f32 v[184:185], v[72:73], v[14:15], v[184:185]
	ds_read_b128 v[12:15], v186 offset:14976
	s_waitcnt lgkmcnt(7)
	v_pk_fma_f32 v[138:139], v[144:145], v[16:17], v[138:139]
	v_pk_fma_f32 v[184:185], v[146:147], v[18:19], v[184:185]
	ds_read_b128 v[16:19], v186 offset:14992
	s_waitcnt lgkmcnt(7)
	v_pk_fma_f32 v[138:139], v[148:149], v[20:21], v[138:139]
	v_pk_fma_f32 v[184:185], v[150:151], v[22:23], v[184:185]
	ds_read_b128 v[20:23], v186 offset:15008
	s_waitcnt lgkmcnt(7)
; #define LAS __attribute__((address_space(3)))
; __device__ __forceinline__ bf16_t f2bf(float f) { unsigned u = __float_as_uint(f); u += 0x7FFFu + ((u >> 16) & 1u); return (bf16_t)(u >> 16); }
; __device__ __forceinline__ void phase_rwkv_ra(const Ctx& c, int p, int l) {
;     ...
;         if (w == 0) {
;             float M[64];
; #pragma unroll
;             for (int tt = 0; tt < 64; ++tt) {
;                 float a4[4] = {(lane == tt) ? 1.f : 0.f, 0.f, 0.f, 0.f};
; #pragma unroll
;                 for (int p4 = 0; p4 < (tt + 3) / 4; ++p4) {
;                     const f32x4 nv = *(const LAS f32x4*)(NfT + tt * 68 + 4 * p4);
; #pragma unroll
;                     for (int e = 0; e < 4; ++e) if (4 * p4 + e < tt) a4[e] += M[4 * p4 + e] * nv[e];
;                 }
;                 const float a = (a4[0] + a4[1]) + (a4[2] + a4[3]);
;                 M[tt] = a;
;                 MinvT[tt * RS + lane] = f2bf(a);
;             }
	v_pk_fma_f32 v[138:139], v[152:153], v[24:25], v[138:139]
	v_pk_fma_f32 v[184:185], v[154:155], v[26:27], v[184:185]
	ds_read_b128 v[24:27], v186 offset:15024
	s_waitcnt lgkmcnt(7)
	v_pk_fma_f32 v[138:139], v[156:157], v[32:33], v[138:139]
	v_pk_fma_f32 v[184:185], v[158:159], v[34:35], v[184:185]
	ds_read_b128 v[32:35], v186 offset:15040
	s_waitcnt lgkmcnt(7)
	v_pk_fma_f32 v[138:139], v[160:161], v[36:37], v[138:139]
	v_pk_fma_f32 v[184:185], v[124:125], v[38:39], v[184:185]
	ds_read_b128 v[36:39], v186 offset:15056
	s_waitcnt lgkmcnt(7)
	v_pk_fma_f32 v[138:139], v[126:127], v[80:81], v[138:139]
	ds_read_b128 v[80:83], v186 offset:15072
	v_add_f32_e32 v187, v138, v139
	v_add_f32_e32 v30, v184, v185
	v_add_f32_e32 v128, v187, v30
	v_cndmask_b32_e64 v84, 0, 1.0, vcc
	v_cvt_pk_bf16_f32 v30, v128, v128
	ds_write_b16 v29, v30 offset:7776
	s_waitcnt lgkmcnt(8)
	v_pk_fma_f32 v[138:139], v[42:43], v[8:9], v[84:85]
	v_cmp_eq_u32_e32 vcc, 56, v88
	v_pk_mul_f32 v[184:185], v[44:45], v[10:11]
	ds_read_b128 v[8:11], v186 offset:15088
	s_waitcnt lgkmcnt(8)
	v_pk_fma_f32 v[138:139], v[46:47], v[12:13], v[138:139]
	v_pk_fma_f32 v[184:185], v[48:49], v[14:15], v[184:185]
	ds_read_b128 v[12:15], v186 offset:15104
	s_waitcnt lgkmcnt(8)
	v_pk_fma_f32 v[138:139], v[50:51], v[16:17], v[138:139]
	v_pk_fma_f32 v[184:185], v[52:53], v[18:19], v[184:185]
	ds_read_b128 v[16:19], v186 offset:15120
	s_waitcnt lgkmcnt(8)
	v_pk_fma_f32 v[138:139], v[54:55], v[20:21], v[138:139]
	v_pk_fma_f32 v[184:185], v[56:57], v[22:23], v[184:185]
	ds_read_b128 v[20:23], v186 offset:15136
	s_waitcnt lgkmcnt(8)
	v_pk_fma_f32 v[138:139], v[58:59], v[24:25], v[138:139]
	v_pk_fma_f32 v[184:185], v[60:61], v[26:27], v[184:185]
	ds_read_b128 v[24:27], v186 offset:15152
	s_waitcnt lgkmcnt(8)
	v_pk_fma_f32 v[138:139], v[62:63], v[32:33], v[138:139]
	v_pk_fma_f32 v[184:185], v[64:65], v[34:35], v[184:185]
	ds_read_b128 v[32:35], v186 offset:15168
	s_waitcnt lgkmcnt(8)
	v_pk_fma_f32 v[138:139], v[66:67], v[36:37], v[138:139]
	v_pk_fma_f32 v[184:185], v[68:69], v[38:39], v[184:185]
	ds_read_b128 v[36:39], v186 offset:15232
	s_waitcnt lgkmcnt(8)
	v_pk_fma_f32 v[138:139], v[70:71], v[80:81], v[138:139]
	v_pk_fma_f32 v[184:185], v[72:73], v[82:83], v[184:185]
	ds_read_b128 v[80:83], v186 offset:15248
	s_waitcnt lgkmcnt(7)
	v_pk_fma_f32 v[138:139], v[144:145], v[8:9], v[138:139]
	v_pk_fma_f32 v[184:185], v[146:147], v[10:11], v[184:185]
	ds_read_b128 v[8:11], v186 offset:15264
	s_waitcnt lgkmcnt(7)
	v_pk_fma_f32 v[138:139], v[148:149], v[12:13], v[138:139]
	v_pk_fma_f32 v[184:185], v[150:151], v[14:15], v[184:185]
	ds_read_b128 v[12:15], v186 offset:15280
	s_waitcnt lgkmcnt(7)
	v_pk_fma_f32 v[138:139], v[152:153], v[16:17], v[138:139]
	v_pk_fma_f32 v[184:185], v[154:155], v[18:19], v[184:185]
	ds_read_b128 v[16:19], v186 offset:15296
	s_waitcnt lgkmcnt(7)
	v_pk_fma_f32 v[138:139], v[156:157], v[20:21], v[138:139]
	v_pk_fma_f32 v[184:185], v[158:159], v[22:23], v[184:185]
	ds_read_b128 v[20:23], v186 offset:15312
	s_waitcnt lgkmcnt(7)
	v_pk_fma_f32 v[138:139], v[160:161], v[24:25], v[138:139]
	v_pk_fma_f32 v[184:185], v[124:125], v[26:27], v[184:185]
	ds_read_b128 v[24:27], v186 offset:15328
	s_waitcnt lgkmcnt(7)
	v_pk_fma_f32 v[138:139], v[126:127], v[32:33], v[138:139]
	v_fmac_f32_e32 v184, v128, v34
	ds_read_b128 v[32:35], v186 offset:15344
	v_add_f32_e32 v187, v138, v139
	v_add_f32_e32 v30, v184, v185
	v_add_f32_e32 v129, v187, v30
	v_cndmask_b32_e64 v84, 0, 1.0, vcc
	v_cvt_pk_bf16_f32 v30, v129, v129
	ds_write_b16 v29, v30 offset:7920
	s_waitcnt lgkmcnt(8)
	v_pk_fma_f32 v[138:139], v[42:43], v[36:37], v[84:85]
	v_cmp_eq_u32_e32 vcc, 57, v88
	v_pk_mul_f32 v[184:185], v[44:45], v[38:39]
	ds_read_b128 v[36:39], v186 offset:15360
	s_waitcnt lgkmcnt(8)
	v_pk_fma_f32 v[138:139], v[46:47], v[80:81], v[138:139]
	v_pk_fma_f32 v[184:185], v[48:49], v[82:83], v[184:185]
	ds_read_b128 v[80:83], v186 offset:15376
	s_waitcnt lgkmcnt(8)
	v_pk_fma_f32 v[138:139], v[50:51], v[8:9], v[138:139]
	v_pk_fma_f32 v[184:185], v[52:53], v[10:11], v[184:185]
	ds_read_b128 v[8:11], v186 offset:15392
	s_waitcnt lgkmcnt(8)
	v_pk_fma_f32 v[138:139], v[54:55], v[12:13], v[138:139]
	v_pk_fma_f32 v[184:185], v[56:57], v[14:15], v[184:185]
	ds_read_b128 v[12:15], v186 offset:15408
	s_waitcnt lgkmcnt(8)
	v_pk_fma_f32 v[138:139], v[58:59], v[16:17], v[138:139]
	v_pk_fma_f32 v[184:185], v[60:61], v[18:19], v[184:185]
	ds_read_b128 v[16:19], v186 offset:15424
	s_waitcnt lgkmcnt(8)
	v_pk_fma_f32 v[138:139], v[62:63], v[20:21], v[138:139]
	v_pk_fma_f32 v[184:185], v[64:65], v[22:23], v[184:185]
	ds_read_b128 v[20:23], v186 offset:15440
	s_waitcnt lgkmcnt(8)
	v_pk_fma_f32 v[138:139], v[66:67], v[24:25], v[138:139]
	v_pk_fma_f32 v[184:185], v[68:69], v[26:27], v[184:185]
	ds_read_b128 v[24:27], v186 offset:15504
	s_waitcnt lgkmcnt(8)
	v_pk_fma_f32 v[138:139], v[70:71], v[32:33], v[138:139]
	v_pk_fma_f32 v[184:185], v[72:73], v[34:35], v[184:185]
	ds_read_b128 v[32:35], v186 offset:15520
	s_waitcnt lgkmcnt(7)
	v_pk_fma_f32 v[138:139], v[144:145], v[36:37], v[138:139]
	v_pk_fma_f32 v[184:185], v[146:147], v[38:39], v[184:185]
	ds_read_b128 v[36:39], v186 offset:15536
	s_waitcnt lgkmcnt(7)
	v_pk_fma_f32 v[138:139], v[148:149], v[80:81], v[138:139]
	v_pk_fma_f32 v[184:185], v[150:151], v[82:83], v[184:185]
	ds_read_b128 v[80:83], v186 offset:15552
	s_waitcnt lgkmcnt(7)
	v_pk_fma_f32 v[138:139], v[152:153], v[8:9], v[138:139]
	v_pk_fma_f32 v[184:185], v[154:155], v[10:11], v[184:185]
	ds_read_b128 v[8:11], v186 offset:15568
	s_waitcnt lgkmcnt(7)
; #define LAS __attribute__((address_space(3)))
; __device__ __forceinline__ bf16_t f2bf(float f) { unsigned u = __float_as_uint(f); u += 0x7FFFu + ((u >> 16) & 1u); return (bf16_t)(u >> 16); }
; __device__ __forceinline__ void phase_rwkv_ra(const Ctx& c, int p, int l) {
;     ...
;         if (w == 0) {
;             float M[64];
; #pragma unroll
;             for (int tt = 0; tt < 64; ++tt) {
;                 float a4[4] = {(lane == tt) ? 1.f : 0.f, 0.f, 0.f, 0.f};
; #pragma unroll
;                 for (int p4 = 0; p4 < (tt + 3) / 4; ++p4) {
;                     const f32x4 nv = *(const LAS f32x4*)(NfT + tt * 68 + 4 * p4);
; #pragma unroll
;                     for (int e = 0; e < 4; ++e) if (4 * p4 + e < tt) a4[e] += M[4 * p4 + e] * nv[e];
;                 }
;                 const float a = (a4[0] + a4[1]) + (a4[2] + a4[3]);
;                 M[tt] = a;
;                 MinvT[tt * RS + lane] = f2bf(a);
;             }
	v_pk_fma_f32 v[138:139], v[156:157], v[12:13], v[138:139]
	v_pk_fma_f32 v[184:185], v[158:159], v[14:15], v[184:185]
	ds_read_b128 v[12:15], v186 offset:15584
	s_waitcnt lgkmcnt(7)
	v_pk_fma_f32 v[138:139], v[160:161], v[16:17], v[138:139]
	v_pk_fma_f32 v[184:185], v[124:125], v[18:19], v[184:185]
	ds_read_b128 v[16:19], v186 offset:15600
	s_waitcnt lgkmcnt(7)
	v_pk_fma_f32 v[138:139], v[126:127], v[20:21], v[138:139]
	v_pk_fma_f32 v[184:185], v[128:129], v[22:23], v[184:185]
	ds_read_b128 v[20:23], v186 offset:15616
	v_add_f32_e32 v187, v138, v139
	v_add_f32_e32 v30, v184, v185
	v_add_f32_e32 v130, v187, v30
	v_cndmask_b32_e64 v84, 0, 1.0, vcc
	v_cvt_pk_bf16_f32 v30, v130, v130
	ds_write_b16 v29, v30 offset:8064
	s_waitcnt lgkmcnt(8)
	v_pk_fma_f32 v[138:139], v[42:43], v[24:25], v[84:85]
	v_cmp_eq_u32_e32 vcc, 58, v88
	v_pk_mul_f32 v[184:185], v[44:45], v[26:27]
	ds_read_b128 v[24:27], v186 offset:15632
	s_waitcnt lgkmcnt(8)
	v_pk_fma_f32 v[138:139], v[46:47], v[32:33], v[138:139]
	v_pk_fma_f32 v[184:185], v[48:49], v[34:35], v[184:185]
	ds_read_b128 v[32:35], v186 offset:15648
	s_waitcnt lgkmcnt(8)
	v_pk_fma_f32 v[138:139], v[50:51], v[36:37], v[138:139]
	v_pk_fma_f32 v[184:185], v[52:53], v[38:39], v[184:185]
	ds_read_b128 v[36:39], v186 offset:15664
	s_waitcnt lgkmcnt(8)
	v_pk_fma_f32 v[138:139], v[54:55], v[80:81], v[138:139]
	v_pk_fma_f32 v[184:185], v[56:57], v[82:83], v[184:185]
	ds_read_b128 v[80:83], v186 offset:15680
	s_waitcnt lgkmcnt(8)
	v_pk_fma_f32 v[138:139], v[58:59], v[8:9], v[138:139]
	v_pk_fma_f32 v[184:185], v[60:61], v[10:11], v[184:185]
	ds_read_b128 v[8:11], v186 offset:15696
	s_waitcnt lgkmcnt(8)
	v_pk_fma_f32 v[138:139], v[62:63], v[12:13], v[138:139]
	v_pk_fma_f32 v[184:185], v[64:65], v[14:15], v[184:185]
	ds_read_b128 v[12:15], v186 offset:15712
	s_waitcnt lgkmcnt(8)
	v_pk_fma_f32 v[138:139], v[66:67], v[16:17], v[138:139]
	v_pk_fma_f32 v[184:185], v[68:69], v[18:19], v[184:185]
	ds_read_b128 v[16:19], v186 offset:15728
	s_waitcnt lgkmcnt(8)
	v_pk_fma_f32 v[138:139], v[70:71], v[20:21], v[138:139]
	v_pk_fma_f32 v[184:185], v[72:73], v[22:23], v[184:185]
	ds_read_b128 v[20:23], v186 offset:15776
	s_waitcnt lgkmcnt(7)
	v_pk_fma_f32 v[138:139], v[144:145], v[24:25], v[138:139]
	v_pk_fma_f32 v[184:185], v[146:147], v[26:27], v[184:185]
	ds_read_b128 v[24:27], v186 offset:15792
	s_waitcnt lgkmcnt(7)
	v_pk_fma_f32 v[138:139], v[148:149], v[32:33], v[138:139]
	v_pk_fma_f32 v[184:185], v[150:151], v[34:35], v[184:185]
	ds_read_b128 v[32:35], v186 offset:15808
	s_waitcnt lgkmcnt(7)
	v_pk_fma_f32 v[138:139], v[152:153], v[36:37], v[138:139]
	v_pk_fma_f32 v[184:185], v[154:155], v[38:39], v[184:185]
	ds_read_b128 v[36:39], v186 offset:15824
	s_waitcnt lgkmcnt(7)
	v_pk_fma_f32 v[138:139], v[156:157], v[80:81], v[138:139]
	v_pk_fma_f32 v[184:185], v[158:159], v[82:83], v[184:185]
	ds_read_b128 v[80:83], v186 offset:15840
	s_waitcnt lgkmcnt(7)
	v_pk_fma_f32 v[138:139], v[160:161], v[8:9], v[138:139]
	v_pk_fma_f32 v[184:185], v[124:125], v[10:11], v[184:185]
	ds_read_b128 v[8:11], v186 offset:15856
	s_waitcnt lgkmcnt(7)
	v_pk_fma_f32 v[138:139], v[126:127], v[12:13], v[138:139]
	v_pk_fma_f32 v[184:185], v[128:129], v[14:15], v[184:185]
	ds_read_b128 v[12:15], v186 offset:15872
	s_waitcnt lgkmcnt(7)
	v_fmac_f32_e32 v138, v130, v16
	ds_read_b128 v[16:19], v186 offset:15888
	v_add_f32_e32 v187, v138, v139
	v_add_f32_e32 v30, v184, v185
	v_add_f32_e32 v131, v187, v30
	v_cndmask_b32_e64 v84, 0, 1.0, vcc
	v_cvt_pk_bf16_f32 v30, v131, v131
	ds_write_b16 v29, v30 offset:8208
	s_waitcnt lgkmcnt(8)
	v_pk_fma_f32 v[138:139], v[42:43], v[20:21], v[84:85]
	v_cmp_eq_u32_e32 vcc, 59, v88
	v_pk_mul_f32 v[184:185], v[44:45], v[22:23]
	ds_read_b128 v[20:23], v186 offset:15904
	s_waitcnt lgkmcnt(8)
	v_pk_fma_f32 v[138:139], v[46:47], v[24:25], v[138:139]
	v_pk_fma_f32 v[184:185], v[48:49], v[26:27], v[184:185]
	ds_read_b128 v[24:27], v186 offset:15920
	s_waitcnt lgkmcnt(8)
	v_pk_fma_f32 v[138:139], v[50:51], v[32:33], v[138:139]
	v_pk_fma_f32 v[184:185], v[52:53], v[34:35], v[184:185]
	ds_read_b128 v[32:35], v186 offset:15936
	s_waitcnt lgkmcnt(8)
	v_pk_fma_f32 v[138:139], v[54:55], v[36:37], v[138:139]
	v_pk_fma_f32 v[184:185], v[56:57], v[38:39], v[184:185]
	ds_read_b128 v[36:39], v186 offset:15952
	s_waitcnt lgkmcnt(8)
	v_pk_fma_f32 v[138:139], v[58:59], v[80:81], v[138:139]
	v_pk_fma_f32 v[184:185], v[60:61], v[82:83], v[184:185]
	ds_read_b128 v[80:83], v186 offset:15968
	s_waitcnt lgkmcnt(8)
	v_pk_fma_f32 v[138:139], v[62:63], v[8:9], v[138:139]
	v_pk_fma_f32 v[184:185], v[64:65], v[10:11], v[184:185]
	ds_read_b128 v[8:11], v186 offset:15984
	s_waitcnt lgkmcnt(8)
	v_pk_fma_f32 v[138:139], v[66:67], v[12:13], v[138:139]
	v_pk_fma_f32 v[184:185], v[68:69], v[14:15], v[184:185]
	ds_read_b128 v[12:15], v186 offset:16000
	s_waitcnt lgkmcnt(8)
	v_pk_fma_f32 v[138:139], v[70:71], v[16:17], v[138:139]
	v_pk_fma_f32 v[184:185], v[72:73], v[18:19], v[184:185]
	ds_read_b128 v[16:19], v186 offset:16048
	s_waitcnt lgkmcnt(7)
	v_pk_fma_f32 v[138:139], v[144:145], v[20:21], v[138:139]
	v_pk_fma_f32 v[184:185], v[146:147], v[22:23], v[184:185]
	ds_read_b128 v[20:23], v186 offset:16064
	s_waitcnt lgkmcnt(7)
	v_pk_fma_f32 v[138:139], v[148:149], v[24:25], v[138:139]
	v_pk_fma_f32 v[184:185], v[150:151], v[26:27], v[184:185]
	ds_read_b128 v[24:27], v186 offset:16080
	s_waitcnt lgkmcnt(7)
	v_pk_fma_f32 v[138:139], v[152:153], v[32:33], v[138:139]
	v_pk_fma_f32 v[184:185], v[154:155], v[34:35], v[184:185]
	ds_read_b128 v[32:35], v186 offset:16096
	s_waitcnt lgkmcnt(7)
; #define LAS __attribute__((address_space(3)))
; __device__ __forceinline__ bf16_t f2bf(float f) { unsigned u = __float_as_uint(f); u += 0x7FFFu + ((u >> 16) & 1u); return (bf16_t)(u >> 16); }
; __device__ __forceinline__ void phase_rwkv_ra(const Ctx& c, int p, int l) {
;     ...
;         if (w == 0) {
;             float M[64];
; #pragma unroll
;             for (int tt = 0; tt < 64; ++tt) {
;                 float a4[4] = {(lane == tt) ? 1.f : 0.f, 0.f, 0.f, 0.f};
; #pragma unroll
;                 for (int p4 = 0; p4 < (tt + 3) / 4; ++p4) {
;                     const f32x4 nv = *(const LAS f32x4*)(NfT + tt * 68 + 4 * p4);
; #pragma unroll
;                     for (int e = 0; e < 4; ++e) if (4 * p4 + e < tt) a4[e] += M[4 * p4 + e] * nv[e];
;                 }
;                 const float a = (a4[0] + a4[1]) + (a4[2] + a4[3]);
;                 M[tt] = a;
;                 MinvT[tt * RS + lane] = f2bf(a);
;             }
	v_pk_fma_f32 v[138:139], v[156:157], v[36:37], v[138:139]
	v_pk_fma_f32 v[184:185], v[158:159], v[38:39], v[184:185]
	ds_read_b128 v[36:39], v186 offset:16112
	s_waitcnt lgkmcnt(7)
	v_pk_fma_f32 v[138:139], v[160:161], v[80:81], v[138:139]
	v_pk_fma_f32 v[184:185], v[124:125], v[82:83], v[184:185]
	ds_read_b128 v[80:83], v186 offset:16128
	s_waitcnt lgkmcnt(7)
	v_pk_fma_f32 v[138:139], v[126:127], v[8:9], v[138:139]
	v_pk_fma_f32 v[184:185], v[128:129], v[10:11], v[184:185]
	ds_read_b128 v[8:11], v186 offset:16144
	s_waitcnt lgkmcnt(7)
	v_pk_fma_f32 v[138:139], v[130:131], v[12:13], v[138:139]
	ds_read_b128 v[12:15], v186 offset:16160
	v_add_f32_e32 v187, v138, v139
	v_add_f32_e32 v30, v184, v185
	v_add_f32_e32 v132, v187, v30
	v_cndmask_b32_e64 v84, 0, 1.0, vcc
	v_cvt_pk_bf16_f32 v30, v132, v132
	ds_write_b16 v29, v30 offset:8352
	s_waitcnt lgkmcnt(8)
	v_pk_fma_f32 v[138:139], v[42:43], v[16:17], v[84:85]
	v_cmp_eq_u32_e32 vcc, 60, v88
	v_pk_mul_f32 v[184:185], v[44:45], v[18:19]
	ds_read_b128 v[16:19], v186 offset:16176
	s_waitcnt lgkmcnt(8)
	v_pk_fma_f32 v[138:139], v[46:47], v[20:21], v[138:139]
	v_pk_fma_f32 v[184:185], v[48:49], v[22:23], v[184:185]
	ds_read_b128 v[20:23], v186 offset:16192
	s_waitcnt lgkmcnt(8)
	v_pk_fma_f32 v[138:139], v[50:51], v[24:25], v[138:139]
	v_pk_fma_f32 v[184:185], v[52:53], v[26:27], v[184:185]
	ds_read_b128 v[24:27], v186 offset:16208
	s_waitcnt lgkmcnt(8)
	v_pk_fma_f32 v[138:139], v[54:55], v[32:33], v[138:139]
	v_pk_fma_f32 v[184:185], v[56:57], v[34:35], v[184:185]
	ds_read_b128 v[32:35], v186 offset:16224
	s_waitcnt lgkmcnt(8)
	v_pk_fma_f32 v[138:139], v[58:59], v[36:37], v[138:139]
	v_pk_fma_f32 v[184:185], v[60:61], v[38:39], v[184:185]
	ds_read_b128 v[36:39], v186 offset:16240
	s_waitcnt lgkmcnt(8)
	v_pk_fma_f32 v[138:139], v[62:63], v[80:81], v[138:139]
	v_pk_fma_f32 v[184:185], v[64:65], v[82:83], v[184:185]
	ds_read_b128 v[80:83], v186 offset:16256
	s_waitcnt lgkmcnt(8)
	v_pk_fma_f32 v[138:139], v[66:67], v[8:9], v[138:139]
	v_pk_fma_f32 v[184:185], v[68:69], v[10:11], v[184:185]
	ds_read_b128 v[8:11], v186 offset:16272
	s_waitcnt lgkmcnt(8)
	v_pk_fma_f32 v[138:139], v[70:71], v[12:13], v[138:139]
	v_pk_fma_f32 v[184:185], v[72:73], v[14:15], v[184:185]
	ds_read_b128 v[12:15], v186 offset:16320
	s_waitcnt lgkmcnt(7)
	v_pk_fma_f32 v[138:139], v[144:145], v[16:17], v[138:139]
	v_pk_fma_f32 v[184:185], v[146:147], v[18:19], v[184:185]
	ds_read_b128 v[16:19], v186 offset:16336
	s_waitcnt lgkmcnt(7)
	v_pk_fma_f32 v[138:139], v[148:149], v[20:21], v[138:139]
	v_pk_fma_f32 v[184:185], v[150:151], v[22:23], v[184:185]
	ds_read_b128 v[20:23], v186 offset:16352
	s_waitcnt lgkmcnt(7)
	v_pk_fma_f32 v[138:139], v[152:153], v[24:25], v[138:139]
	v_pk_fma_f32 v[184:185], v[154:155], v[26:27], v[184:185]
	ds_read_b128 v[24:27], v186 offset:16368
	s_waitcnt lgkmcnt(7)
	v_pk_fma_f32 v[138:139], v[156:157], v[32:33], v[138:139]
	v_pk_fma_f32 v[184:185], v[158:159], v[34:35], v[184:185]
	ds_read_b128 v[32:35], v186 offset:16384
	s_waitcnt lgkmcnt(7)
	v_pk_fma_f32 v[138:139], v[160:161], v[36:37], v[138:139]
	v_pk_fma_f32 v[184:185], v[124:125], v[38:39], v[184:185]
	ds_read_b128 v[36:39], v186 offset:16400
	s_waitcnt lgkmcnt(7)
	v_pk_fma_f32 v[138:139], v[126:127], v[80:81], v[138:139]
	v_pk_fma_f32 v[184:185], v[128:129], v[82:83], v[184:185]
	ds_read_b128 v[80:83], v186 offset:16416
	s_waitcnt lgkmcnt(7)
	v_pk_fma_f32 v[138:139], v[130:131], v[8:9], v[138:139]
	v_fmac_f32_e32 v184, v132, v10
	ds_read_b128 v[8:11], v186 offset:16432
	v_add_f32_e32 v187, v138, v139
	v_add_f32_e32 v30, v184, v185
	v_add_f32_e32 v133, v187, v30
	v_cndmask_b32_e64 v84, 0, 1.0, vcc
	v_cvt_pk_bf16_f32 v30, v133, v133
	ds_write_b16 v29, v30 offset:8496
	s_waitcnt lgkmcnt(8)
	v_pk_fma_f32 v[138:139], v[42:43], v[12:13], v[84:85]
	v_cmp_eq_u32_e32 vcc, 61, v88
	v_pk_mul_f32 v[184:185], v[44:45], v[14:15]
	ds_read_b128 v[12:15], v186 offset:16448
	s_waitcnt lgkmcnt(8)
	v_pk_fma_f32 v[138:139], v[46:47], v[16:17], v[138:139]
	v_pk_fma_f32 v[184:185], v[48:49], v[18:19], v[184:185]
	ds_read_b128 v[16:19], v186 offset:16464
	s_waitcnt lgkmcnt(8)
	v_pk_fma_f32 v[138:139], v[50:51], v[20:21], v[138:139]
	v_pk_fma_f32 v[184:185], v[52:53], v[22:23], v[184:185]
	ds_read_b128 v[20:23], v186 offset:16480
	s_waitcnt lgkmcnt(8)
	v_pk_fma_f32 v[138:139], v[54:55], v[24:25], v[138:139]
	v_pk_fma_f32 v[184:185], v[56:57], v[26:27], v[184:185]
	ds_read_b128 v[24:27], v186 offset:16496
	s_waitcnt lgkmcnt(8)
	v_pk_fma_f32 v[138:139], v[58:59], v[32:33], v[138:139]
	v_pk_fma_f32 v[184:185], v[60:61], v[34:35], v[184:185]
	ds_read_b128 v[32:35], v186 offset:16512
	s_waitcnt lgkmcnt(8)
	v_pk_fma_f32 v[138:139], v[62:63], v[36:37], v[138:139]
	v_pk_fma_f32 v[184:185], v[64:65], v[38:39], v[184:185]
	ds_read_b128 v[36:39], v186 offset:16528
	s_waitcnt lgkmcnt(8)
	v_pk_fma_f32 v[138:139], v[66:67], v[80:81], v[138:139]
	v_pk_fma_f32 v[184:185], v[68:69], v[82:83], v[184:185]
	ds_read_b128 v[80:83], v186 offset:16544
	s_waitcnt lgkmcnt(8)
	v_pk_fma_f32 v[138:139], v[70:71], v[8:9], v[138:139]
	v_pk_fma_f32 v[184:185], v[72:73], v[10:11], v[184:185]
	ds_read_b128 v[8:11], v186 offset:16592
	s_waitcnt lgkmcnt(7)
	v_pk_fma_f32 v[138:139], v[144:145], v[12:13], v[138:139]
	v_pk_fma_f32 v[184:185], v[146:147], v[14:15], v[184:185]
	ds_read_b128 v[12:15], v186 offset:16608
	s_waitcnt lgkmcnt(7)
	v_pk_fma_f32 v[138:139], v[148:149], v[16:17], v[138:139]
	v_pk_fma_f32 v[184:185], v[150:151], v[18:19], v[184:185]
	ds_read_b128 v[16:19], v186 offset:16624
	s_waitcnt lgkmcnt(7)
; #define LAS __attribute__((address_space(3)))
; __device__ __forceinline__ bf16_t f2bf(float f) { unsigned u = __float_as_uint(f); u += 0x7FFFu + ((u >> 16) & 1u); return (bf16_t)(u >> 16); }
; __device__ __forceinline__ void phase_rwkv_ra(const Ctx& c, int p, int l) {
;     ...
;         if (w == 0) {
;             float M[64];
; #pragma unroll
;             for (int tt = 0; tt < 64; ++tt) {
;                 float a4[4] = {(lane == tt) ? 1.f : 0.f, 0.f, 0.f, 0.f};
; #pragma unroll
;                 for (int p4 = 0; p4 < (tt + 3) / 4; ++p4) {
;                     const f32x4 nv = *(const LAS f32x4*)(NfT + tt * 68 + 4 * p4);
; #pragma unroll
;                     for (int e = 0; e < 4; ++e) if (4 * p4 + e < tt) a4[e] += M[4 * p4 + e] * nv[e];
;                 }
;                 const float a = (a4[0] + a4[1]) + (a4[2] + a4[3]);
;                 M[tt] = a;
;                 MinvT[tt * RS + lane] = f2bf(a);
;             }
	v_pk_fma_f32 v[138:139], v[152:153], v[20:21], v[138:139]
	v_pk_fma_f32 v[184:185], v[154:155], v[22:23], v[184:185]
	ds_read_b128 v[20:23], v186 offset:16640
	s_waitcnt lgkmcnt(7)
	v_pk_fma_f32 v[138:139], v[156:157], v[24:25], v[138:139]
	v_pk_fma_f32 v[184:185], v[158:159], v[26:27], v[184:185]
	ds_read_b128 v[24:27], v186 offset:16656
	s_waitcnt lgkmcnt(7)
	v_pk_fma_f32 v[138:139], v[160:161], v[32:33], v[138:139]
	v_pk_fma_f32 v[184:185], v[124:125], v[34:35], v[184:185]
	ds_read_b128 v[32:35], v186 offset:16672
	s_waitcnt lgkmcnt(7)
	v_pk_fma_f32 v[138:139], v[126:127], v[36:37], v[138:139]
	v_pk_fma_f32 v[184:185], v[128:129], v[38:39], v[184:185]
	ds_read_b128 v[36:39], v186 offset:16688
	s_waitcnt lgkmcnt(7)
	v_pk_fma_f32 v[138:139], v[130:131], v[80:81], v[138:139]
	v_pk_fma_f32 v[184:185], v[132:133], v[82:83], v[184:185]
	ds_read_b128 v[80:83], v186 offset:16704
	v_add_f32_e32 v187, v138, v139
	v_add_f32_e32 v30, v184, v185
	v_add_f32_e32 v134, v187, v30
	v_cndmask_b32_e64 v84, 0, 1.0, vcc
	v_cvt_pk_bf16_f32 v30, v134, v134
	ds_write_b16 v29, v30 offset:8640
	s_waitcnt lgkmcnt(8)
	v_pk_fma_f32 v[138:139], v[42:43], v[8:9], v[84:85]
	v_cmp_eq_u32_e32 vcc, 62, v88
	v_pk_mul_f32 v[184:185], v[44:45], v[10:11]
	ds_read_b128 v[8:11], v186 offset:16720
	s_waitcnt lgkmcnt(8)
	v_pk_fma_f32 v[138:139], v[46:47], v[12:13], v[138:139]
	v_pk_fma_f32 v[184:185], v[48:49], v[14:15], v[184:185]
	ds_read_b128 v[12:15], v186 offset:16736
	s_waitcnt lgkmcnt(8)
	v_pk_fma_f32 v[138:139], v[50:51], v[16:17], v[138:139]
	v_pk_fma_f32 v[184:185], v[52:53], v[18:19], v[184:185]
	ds_read_b128 v[16:19], v186 offset:16752
	s_waitcnt lgkmcnt(8)
	v_pk_fma_f32 v[138:139], v[54:55], v[20:21], v[138:139]
	v_pk_fma_f32 v[184:185], v[56:57], v[22:23], v[184:185]
	ds_read_b128 v[20:23], v186 offset:16768
	s_waitcnt lgkmcnt(8)
	v_pk_fma_f32 v[138:139], v[58:59], v[24:25], v[138:139]
	v_pk_fma_f32 v[184:185], v[60:61], v[26:27], v[184:185]
	ds_read_b128 v[24:27], v186 offset:16784
	s_waitcnt lgkmcnt(8)
	v_pk_fma_f32 v[138:139], v[62:63], v[32:33], v[138:139]
	v_pk_fma_f32 v[184:185], v[64:65], v[34:35], v[184:185]
	ds_read_b128 v[32:35], v186 offset:16800
	s_waitcnt lgkmcnt(8)
	v_pk_fma_f32 v[138:139], v[66:67], v[36:37], v[138:139]
	v_pk_fma_f32 v[184:185], v[68:69], v[38:39], v[184:185]
	ds_read_b128 v[36:39], v186 offset:16816
	s_waitcnt lgkmcnt(8)
	v_pk_fma_f32 v[138:139], v[70:71], v[80:81], v[138:139]
	v_pk_fma_f32 v[184:185], v[72:73], v[82:83], v[184:185]
	ds_read_b128 v[80:83], v186 offset:16832
	s_waitcnt lgkmcnt(7)
	v_pk_fma_f32 v[138:139], v[144:145], v[8:9], v[138:139]
	v_pk_fma_f32 v[184:185], v[146:147], v[10:11], v[184:185]
	ds_read_b128 v[8:11], v186 offset:16864
	s_waitcnt lgkmcnt(7)
	v_pk_fma_f32 v[138:139], v[148:149], v[12:13], v[138:139]
	v_pk_fma_f32 v[184:185], v[150:151], v[14:15], v[184:185]
	ds_read_b128 v[12:15], v186 offset:16880
	s_waitcnt lgkmcnt(7)
	v_pk_fma_f32 v[138:139], v[152:153], v[16:17], v[138:139]
	v_pk_fma_f32 v[184:185], v[154:155], v[18:19], v[184:185]
	ds_read_b128 v[16:19], v186 offset:16896
	s_waitcnt lgkmcnt(7)
	v_pk_fma_f32 v[138:139], v[156:157], v[20:21], v[138:139]
	v_pk_fma_f32 v[184:185], v[158:159], v[22:23], v[184:185]
	ds_read_b128 v[20:23], v186 offset:16912
	s_waitcnt lgkmcnt(7)
	v_pk_fma_f32 v[138:139], v[160:161], v[24:25], v[138:139]
	v_pk_fma_f32 v[184:185], v[124:125], v[26:27], v[184:185]
	ds_read_b128 v[24:27], v186 offset:16928
	s_waitcnt lgkmcnt(7)
	v_pk_fma_f32 v[138:139], v[126:127], v[32:33], v[138:139]
	v_pk_fma_f32 v[184:185], v[128:129], v[34:35], v[184:185]
	ds_read_b128 v[32:35], v186 offset:16944
	s_waitcnt lgkmcnt(7)
	v_pk_fma_f32 v[138:139], v[130:131], v[36:37], v[138:139]
	v_pk_fma_f32 v[184:185], v[132:133], v[38:39], v[184:185]
	ds_read_b128 v[36:39], v186 offset:16960
	s_waitcnt lgkmcnt(7)
	v_fmac_f32_e32 v138, v134, v80
	ds_read_b128 v[80:83], v186 offset:16976
	v_add_f32_e32 v187, v138, v139
	v_add_f32_e32 v30, v184, v185
	v_add_f32_e32 v135, v187, v30
	v_cndmask_b32_e64 v84, 0, 1.0, vcc
	v_cvt_pk_bf16_f32 v30, v135, v135
	ds_write_b16 v29, v30 offset:8784
	s_waitcnt lgkmcnt(8)
	v_pk_fma_f32 v[138:139], v[42:43], v[8:9], v[84:85]
	v_cmp_eq_u32_e32 vcc, 63, v88
	v_pk_mul_f32 v[184:185], v[44:45], v[10:11]
	ds_read_b128 v[8:11], v186 offset:16992
	s_waitcnt lgkmcnt(8)
	v_pk_fma_f32 v[138:139], v[46:47], v[12:13], v[138:139]
	v_pk_fma_f32 v[184:185], v[48:49], v[14:15], v[184:185]
	ds_read_b128 v[12:15], v186 offset:17008
	s_waitcnt lgkmcnt(8)
	v_pk_fma_f32 v[138:139], v[50:51], v[16:17], v[138:139]
	v_pk_fma_f32 v[184:185], v[52:53], v[18:19], v[184:185]
	ds_read_b128 v[16:19], v186 offset:17024
	s_waitcnt lgkmcnt(8)
	v_pk_fma_f32 v[138:139], v[54:55], v[20:21], v[138:139]
	v_pk_fma_f32 v[184:185], v[56:57], v[22:23], v[184:185]
	ds_read_b128 v[20:23], v186 offset:17040
	s_waitcnt lgkmcnt(8)
; #define LAS __attribute__((address_space(3)))
; __device__ __forceinline__ bf16_t f2bf(float f) { unsigned u = __float_as_uint(f); u += 0x7FFFu + ((u >> 16) & 1u); return (bf16_t)(u >> 16); }
; __device__ __forceinline__ void phase_rwkv_ra(const Ctx& c, int p, int l) {
;     ...
;         if (w == 0) {
;             float M[64];
; #pragma unroll
;             for (int tt = 0; tt < 64; ++tt) {
;                 float a4[4] = {(lane == tt) ? 1.f : 0.f, 0.f, 0.f, 0.f};
; #pragma unroll
;                 for (int p4 = 0; p4 < (tt + 3) / 4; ++p4) {
;                     const f32x4 nv = *(const LAS f32x4*)(NfT + tt * 68 + 4 * p4);
; #pragma unroll
;                     for (int e = 0; e < 4; ++e) if (4 * p4 + e < tt) a4[e] += M[4 * p4 + e] * nv[e];
;                 }
;                 const float a = (a4[0] + a4[1]) + (a4[2] + a4[3]);
;                 M[tt] = a;
;                 MinvT[tt * RS + lane] = f2bf(a);
;             }
	v_pk_fma_f32 v[138:139], v[58:59], v[24:25], v[138:139]
	v_pk_fma_f32 v[184:185], v[60:61], v[26:27], v[184:185]
	ds_read_b128 v[24:27], v186 offset:17056
	s_waitcnt lgkmcnt(8)
	v_pk_fma_f32 v[138:139], v[62:63], v[32:33], v[138:139]
	v_pk_fma_f32 v[184:185], v[64:65], v[34:35], v[184:185]
	ds_read_b128 v[32:35], v186 offset:17072
	s_waitcnt lgkmcnt(8)
	v_pk_fma_f32 v[138:139], v[66:67], v[36:37], v[138:139]
	v_pk_fma_f32 v[184:185], v[68:69], v[38:39], v[184:185]
	ds_read_b128 v[36:39], v186 offset:17088
	s_waitcnt lgkmcnt(8)
	v_pk_fma_f32 v[138:139], v[70:71], v[80:81], v[138:139]
	v_pk_fma_f32 v[184:185], v[72:73], v[82:83], v[184:185]
	ds_read_b128 v[80:83], v186 offset:17104
	s_waitcnt lgkmcnt(7)
	v_pk_fma_f32 v[138:139], v[144:145], v[8:9], v[138:139]
	v_pk_fma_f32 v[184:185], v[146:147], v[10:11], v[184:185]
	ds_read_b128 v[8:11], v186 offset:17136
	s_waitcnt lgkmcnt(7)
	v_pk_fma_f32 v[138:139], v[148:149], v[12:13], v[138:139]
	v_pk_fma_f32 v[184:185], v[150:151], v[14:15], v[184:185]
	ds_read_b128 v[12:15], v186 offset:17152
	s_waitcnt lgkmcnt(7)
	v_pk_fma_f32 v[138:139], v[152:153], v[16:17], v[138:139]
	v_pk_fma_f32 v[184:185], v[154:155], v[18:19], v[184:185]
	ds_read_b128 v[16:19], v186 offset:17168
	s_waitcnt lgkmcnt(7)
	v_pk_fma_f32 v[138:139], v[156:157], v[20:21], v[138:139]
	v_pk_fma_f32 v[184:185], v[158:159], v[22:23], v[184:185]
	ds_read_b128 v[20:23], v186 offset:17184
	s_waitcnt lgkmcnt(7)
	v_pk_fma_f32 v[138:139], v[160:161], v[24:25], v[138:139]
	v_pk_fma_f32 v[184:185], v[124:125], v[26:27], v[184:185]
	ds_read_b128 v[24:27], v186 offset:17200
	s_waitcnt lgkmcnt(7)
	v_pk_fma_f32 v[138:139], v[126:127], v[32:33], v[138:139]
	v_pk_fma_f32 v[184:185], v[128:129], v[34:35], v[184:185]
	ds_read_b128 v[32:35], v186 offset:17216
	s_waitcnt lgkmcnt(7)
	v_pk_fma_f32 v[138:139], v[130:131], v[36:37], v[138:139]
	v_pk_fma_f32 v[184:185], v[132:133], v[38:39], v[184:185]
	ds_read_b128 v[36:39], v186 offset:17232
	s_waitcnt lgkmcnt(7)
	v_pk_fma_f32 v[138:139], v[134:135], v[80:81], v[138:139]
	ds_read_b128 v[80:83], v186 offset:17248
	v_add_f32_e32 v187, v138, v139
	v_add_f32_e32 v30, v184, v185
	v_add_f32_e32 v136, v187, v30
	v_cndmask_b32_e64 v84, 0, 1.0, vcc
	v_cvt_pk_bf16_f32 v30, v136, v136
	ds_write_b16 v29, v30 offset:8928
	s_waitcnt lgkmcnt(8)
	v_pk_fma_f32 v[138:139], v[42:43], v[8:9], v[84:85]
	v_pk_mul_f32 v[184:185], v[44:45], v[10:11]
	ds_read_b128 v[8:11], v186 offset:17264
	s_waitcnt lgkmcnt(8)
	v_pk_fma_f32 v[138:139], v[46:47], v[12:13], v[138:139]
	v_pk_fma_f32 v[184:185], v[48:49], v[14:15], v[184:185]
	ds_read_b128 v[12:15], v186 offset:17280
	s_waitcnt lgkmcnt(8)
	v_pk_fma_f32 v[138:139], v[50:51], v[16:17], v[138:139]
	v_pk_fma_f32 v[184:185], v[52:53], v[18:19], v[184:185]
	ds_read_b128 v[16:19], v186 offset:17296
	s_waitcnt lgkmcnt(8)
	v_pk_fma_f32 v[138:139], v[54:55], v[20:21], v[138:139]
	v_pk_fma_f32 v[184:185], v[56:57], v[22:23], v[184:185]
	ds_read_b128 v[20:23], v186 offset:17312
	s_waitcnt lgkmcnt(8)
	v_pk_fma_f32 v[138:139], v[58:59], v[24:25], v[138:139]
	v_pk_fma_f32 v[184:185], v[60:61], v[26:27], v[184:185]
	ds_read_b128 v[24:27], v186 offset:17328
	s_waitcnt lgkmcnt(8)
	v_pk_fma_f32 v[138:139], v[62:63], v[32:33], v[138:139]
	v_pk_fma_f32 v[184:185], v[64:65], v[34:35], v[184:185]
	ds_read_b128 v[32:35], v186 offset:17344
	s_waitcnt lgkmcnt(8)
	v_pk_fma_f32 v[138:139], v[66:67], v[36:37], v[138:139]
	v_pk_fma_f32 v[184:185], v[68:69], v[38:39], v[184:185]
	ds_read_b128 v[36:39], v186 offset:17360
	s_waitcnt lgkmcnt(8)
	v_pk_fma_f32 v[138:139], v[70:71], v[80:81], v[138:139]
	v_pk_fma_f32 v[184:185], v[72:73], v[82:83], v[184:185]
	ds_read_b128 v[80:83], v186 offset:17376
	s_waitcnt lgkmcnt(7)
	v_pk_fma_f32 v[138:139], v[144:145], v[8:9], v[138:139]
	v_pk_fma_f32 v[184:185], v[146:147], v[10:11], v[184:185]
	s_waitcnt lgkmcnt(6)
	v_pk_fma_f32 v[138:139], v[148:149], v[12:13], v[138:139]
	v_pk_fma_f32 v[184:185], v[150:151], v[14:15], v[184:185]
	s_waitcnt lgkmcnt(5)
	v_pk_fma_f32 v[138:139], v[152:153], v[16:17], v[138:139]
	v_pk_fma_f32 v[184:185], v[154:155], v[18:19], v[184:185]
	s_waitcnt lgkmcnt(4)
	v_pk_fma_f32 v[138:139], v[156:157], v[20:21], v[138:139]
	v_pk_fma_f32 v[184:185], v[158:159], v[22:23], v[184:185]
	s_waitcnt lgkmcnt(3)
	v_pk_fma_f32 v[138:139], v[160:161], v[24:25], v[138:139]
	v_pk_fma_f32 v[184:185], v[124:125], v[26:27], v[184:185]
	s_waitcnt lgkmcnt(2)
	v_pk_fma_f32 v[138:139], v[126:127], v[32:33], v[138:139]
	v_pk_fma_f32 v[184:185], v[128:129], v[34:35], v[184:185]
	s_waitcnt lgkmcnt(1)
	v_pk_fma_f32 v[138:139], v[130:131], v[36:37], v[138:139]
	v_pk_fma_f32 v[184:185], v[132:133], v[38:39], v[184:185]
	s_waitcnt lgkmcnt(0)
	v_pk_fma_f32 v[138:139], v[134:135], v[80:81], v[138:139]
	v_fmac_f32_e32 v184, v136, v82
	v_add_f32_e32 v187, v138, v139
	v_add_f32_e32 v30, v184, v185
	v_add_f32_e32 v137, v187, v30
	v_cvt_pk_bf16_f32 v30, v137, v137
	ds_write_b16 v29, v30 offset:9072
